# GEMM load segments: m0 wait state filled by the address computation instead of s_nop (52 sites)
# baseline (speedup 1.0000x reference)
; #define PG8_STAGE(bufoff, gbase, voff) do { _Pragma("unroll") for (int _i = 0; _i < 2; ++_i) \
;         __builtin_amdgcn_global_load_lds((const unsigned*)((const char*)(gbase) + (voff)[_i]), (LAS unsigned*)(lds + (bufoff) + ldsw + _i * 8192), 16, 0, 0); } while (0)
; #define PG8_LDA(dst, b, h) do { _Pragma("unroll") for (int m = 0; m < 4; ++m) _Pragma("unroll") for (int k = 0; k < 2; ++k) dst[m][k] = *(const LAS bf16x8*)(lds + PG8_SA(b, h) + aoff + m * 2048 + k * 1024); } while (0)
; #define PG8_LDB(dst, b, h) do { _Pragma("unroll") for (int n = 0; n < 2; ++n) _Pragma("unroll") for (int k = 0; k < 2; ++k) dst[n][k] = *(const LAS bf16x8*)(lds + PG8_SB(b, h) + boff + n * 2048 + k * 1024); } while (0)
; #define PG8_MMA(ai, bj, At, Bt) do { __builtin_amdgcn_s_setprio(1); _Pragma("unroll") for (int m = 0; m < 4; ++m) _Pragma("unroll") for (int n = 0; n < 2; ++n) _Pragma("unroll") for (int k = 0; k < 2; ++k) \
;         acc[ai][bj][m][n] = __builtin_amdgcn_mfma_f32_16x16x32_bf16(Bt[n][k], At[m][k], acc[ai][bj][m][n], 0, 0, 0); __builtin_amdgcn_s_setprio(0); } while (0)
; #define PG8_WAIT_V(n) asm volatile("s_waitcnt vmcnt(" #n ")" ::: "memory")
; #define PG8_WAIT_L(n) asm volatile("s_waitcnt lgkmcnt(" #n ")" ::: "memory")
; #define PG8_BAR __builtin_amdgcn_s_barrier()
; #define PG8_SCHED __builtin_amdgcn_sched_barrier(0)
; template <class Epi, class Sched>
; __device__ __forceinline__ void gemm_phase(LAS unsigned char* lds, const Gemm g, const Sched S, const Epi E, const int tid) {
;     ...
;             const bool last = (t == nt - 2);
;             const char* a1 = cA + (size_t)(t + 1) * kstep;
;             const char* a2 = last ? nA : cA + (size_t)(t + 2) * kstep; const char* b2 = last ? nB : cB + (size_t)(t + 2) * kstep;
;             const char* a3 = a2 + kstep; const char* b3 = b2 + kstep;
;             PG8_LDB(B0, 0, 0); PG8_LDB(B1, 0, 1); PG8_SCHED; PG8_LDA(At, 0, 0); PG8_STAGE(PG8_SA(1, 1), a1 + hstepA, voffA);
;             PG8_WAIT_V(8); PG8_WAIT_L(0); PG8_BAR; PG8_MMA(0, 0, At, B0); PG8_MMA(0, 1, At, B1); PG8_BAR; PG8_SCHED;
;             PG8_LDA(At, 0, 1); PG8_STAGE(PG8_SB(0, 0), b2, voffB); PG8_STAGE(PG8_SB(0, 1), b2 + hstepB, voffB); PG8_STAGE(PG8_SA(0, 0), a2, voffA);
;             PG8_WAIT_V(8); PG8_WAIT_L(0); PG8_BAR; PG8_MMA(1, 0, At, B0); PG8_MMA(1, 1, At, B1); PG8_BAR; PG8_SCHED;
.LBB0_299:
	s_add_u32 s10, s22, 0xfffc0080
	s_addc_u32 s11, s23, -1
	s_add_i32 s44, 0, 0x10000
	s_cmp_eq_u32 vcc_hi, 28
	s_cselect_b32 s29, s93, s11
	s_cselect_b32 s28, s94, s10
	v_add_u32_e32 v154, s44, v167
	s_cselect_b32 s27, s95, vcc_lo
	s_cselect_b32 s26, s96, s97
	s_add_i32 s45, 0, 0x14000
	ds_read_b128 v[98:101], v154
	ds_read_b128 v[102:105], v154 offset:1024
	ds_read_b128 v[150:153], v154 offset:2048
	ds_read_b128 v[180:183], v154 offset:3072
	v_add_u32_e32 v154, s45, v167
	ds_read_b128 v[184:187], v154
	ds_read_b128 v[188:191], v154 offset:1024
	ds_read_b128 v[192:195], v154 offset:2048
	ds_read_b128 v[196:199], v154 offset:3072
	v_lshl_add_u64 v[154:155], s[22:23], 0, v[148:149]
	s_add_i32 m0, s47, 0xc000
	ds_read_b128 v[200:203], v179
	ds_read_b128 v[204:207], v179 offset:1024
	ds_read_b128 v[208:211], v179 offset:2048
	ds_read_b128 v[212:215], v179 offset:3072
	ds_read_b128 v[216:219], v179 offset:4096
	ds_read_b128 v[220:223], v179 offset:5120
	ds_read_b128 v[224:227], v179 offset:6144
	ds_read_b128 v[228:231], v179 offset:7168
	global_load_lds_dwordx4 v[154:155], off
	s_add_i32 m0, s47, 0xe000
	v_lshl_add_u64 v[154:155], s[22:23], 0, v[146:147]
	global_load_lds_dwordx4 v[154:155], off
	s_waitcnt vmcnt(8)
	s_waitcnt lgkmcnt(0)
	s_barrier
	s_setprio 1
	v_mfma_f32_16x16x32_bf16 v[134:137], v[98:101], v[200:203], v[134:137]
	v_mfma_f32_16x16x32_bf16 v[130:133], v[150:153], v[200:203], v[130:133]
	v_mfma_f32_16x16x32_bf16 v[126:129], v[98:101], v[208:211], v[126:129]
	v_mfma_f32_16x16x32_bf16 v[122:125], v[150:153], v[208:211], v[122:125]
	v_mfma_f32_16x16x32_bf16 v[118:121], v[98:101], v[216:219], v[118:121]
	v_mfma_f32_16x16x32_bf16 v[114:117], v[150:153], v[216:219], v[114:117]
	v_mfma_f32_16x16x32_bf16 v[110:113], v[98:101], v[224:227], v[110:113]
	v_mfma_f32_16x16x32_bf16 v[106:109], v[150:153], v[224:227], v[106:109]
	v_mfma_f32_16x16x32_bf16 v[134:137], v[102:105], v[204:207], v[134:137]
	v_mfma_f32_16x16x32_bf16 v[130:133], v[180:183], v[204:207], v[130:133]
	v_mfma_f32_16x16x32_bf16 v[126:129], v[102:105], v[212:215], v[126:129]
	v_mfma_f32_16x16x32_bf16 v[122:125], v[180:183], v[212:215], v[122:125]
	v_mfma_f32_16x16x32_bf16 v[118:121], v[102:105], v[220:223], v[118:121]
	v_mfma_f32_16x16x32_bf16 v[114:117], v[180:183], v[220:223], v[114:117]
	v_mfma_f32_16x16x32_bf16 v[110:113], v[102:105], v[228:231], v[110:113]
	v_mfma_f32_16x16x32_bf16 v[106:109], v[180:183], v[228:231], v[106:109]
	v_mfma_f32_16x16x32_bf16 v[62:65], v[184:187], v[200:203], v[62:65]
	v_mfma_f32_16x16x32_bf16 v[58:61], v[192:195], v[200:203], v[58:61]
	v_mfma_f32_16x16x32_bf16 v[54:57], v[184:187], v[208:211], v[54:57]
	v_mfma_f32_16x16x32_bf16 v[50:53], v[192:195], v[208:211], v[50:53]
	v_mfma_f32_16x16x32_bf16 v[46:49], v[184:187], v[216:219], v[46:49]
	v_mfma_f32_16x16x32_bf16 v[42:45], v[192:195], v[216:219], v[42:45]
	v_mfma_f32_16x16x32_bf16 v[38:41], v[184:187], v[224:227], v[38:41]
	v_mfma_f32_16x16x32_bf16 v[34:37], v[192:195], v[224:227], v[34:37]
	v_mfma_f32_16x16x32_bf16 v[62:65], v[188:191], v[204:207], v[62:65]
	v_mfma_f32_16x16x32_bf16 v[58:61], v[196:199], v[204:207], v[58:61]
	v_mfma_f32_16x16x32_bf16 v[54:57], v[188:191], v[212:215], v[54:57]
	v_mfma_f32_16x16x32_bf16 v[50:53], v[196:199], v[212:215], v[50:53]
	v_mfma_f32_16x16x32_bf16 v[46:49], v[188:191], v[220:223], v[46:49]
	v_mfma_f32_16x16x32_bf16 v[42:45], v[196:199], v[220:223], v[42:45]
	v_mfma_f32_16x16x32_bf16 v[38:41], v[188:191], v[228:231], v[38:41]
	v_mfma_f32_16x16x32_bf16 v[34:37], v[196:199], v[228:231], v[34:37]
	s_setprio 0
	s_barrier
	s_add_i32 s10, s44, s46
	v_lshl_add_u64 v[154:155], s[26:27], 0, v[142:143]
	s_mov_b32 m0, s10
	ds_read_b128 v[200:203], v179 offset:16384
	ds_read_b128 v[204:207], v179 offset:17408
	ds_read_b128 v[208:211], v179 offset:18432
	ds_read_b128 v[212:215], v179 offset:19456
	ds_read_b128 v[216:219], v179 offset:20480
	ds_read_b128 v[220:223], v179 offset:21504
	ds_read_b128 v[224:227], v179 offset:22528
	ds_read_b128 v[228:231], v179 offset:23552
	global_load_lds_dwordx4 v[154:155], off
	s_add_i32 m0, s10, 0x2000
	s_add_u32 s10, s26, 0x80000
	v_lshl_add_u64 v[232:233], s[26:27], 0, v[138:139]
	s_addc_u32 s11, s27, 0
	s_add_i32 s45, s45, s46
	global_load_lds_dwordx4 v[232:233], off
	v_lshl_add_u64 v[234:235], s[10:11], 0, v[142:143]
	s_mov_b32 m0, s45
	v_lshl_add_u64 v[246:247], s[28:29], 0, v[140:141]
	global_load_lds_dwordx4 v[234:235], off
	s_add_i32 m0, s45, 0x2000
	v_lshl_add_u64 v[234:235], s[10:11], 0, v[138:139]
	global_load_lds_dwordx4 v[234:235], off
	s_mov_b32 m0, s47
	v_lshl_add_u64 v[234:235], s[28:29], 0, v[144:145]
	global_load_lds_dwordx4 v[234:235], off
	s_mov_b32 m0, s48
	s_nop 0
	global_load_lds_dwordx4 v[246:247], off
	s_waitcnt vmcnt(8)
	s_waitcnt lgkmcnt(0)
	s_barrier
; #define PG8_STAGE(bufoff, gbase, voff) do { _Pragma("unroll") for (int _i = 0; _i < 2; ++_i) \
;         __builtin_amdgcn_global_load_lds((const unsigned*)((const char*)(gbase) + (voff)[_i]), (LAS unsigned*)(lds + (bufoff) + ldsw + _i * 8192), 16, 0, 0); } while (0)
; #define PG8_LDA(dst, b, h) do { _Pragma("unroll") for (int m = 0; m < 4; ++m) _Pragma("unroll") for (int k = 0; k < 2; ++k) dst[m][k] = *(const LAS bf16x8*)(lds + PG8_SA(b, h) + aoff + m * 2048 + k * 1024); } while (0)
; #define PG8_LDB(dst, b, h) do { _Pragma("unroll") for (int n = 0; n < 2; ++n) _Pragma("unroll") for (int k = 0; k < 2; ++k) dst[n][k] = *(const LAS bf16x8*)(lds + PG8_SB(b, h) + boff + n * 2048 + k * 1024); } while (0)
; #define PG8_MMA(ai, bj, At, Bt) do { __builtin_amdgcn_s_setprio(1); _Pragma("unroll") for (int m = 0; m < 4; ++m) _Pragma("unroll") for (int n = 0; n < 2; ++n) _Pragma("unroll") for (int k = 0; k < 2; ++k) \
;         acc[ai][bj][m][n] = __builtin_amdgcn_mfma_f32_16x16x32_bf16(Bt[n][k], At[m][k], acc[ai][bj][m][n], 0, 0, 0); __builtin_amdgcn_s_setprio(0); } while (0)
; #define PG8_WAIT_V(n) asm volatile("s_waitcnt vmcnt(" #n ")" ::: "memory")
; #define PG8_WAIT_L(n) asm volatile("s_waitcnt lgkmcnt(" #n ")" ::: "memory")
; #define PG8_BAR __builtin_amdgcn_s_barrier()
; #define PG8_SCHED __builtin_amdgcn_sched_barrier(0)
; template <class Epi, class Sched>
; __device__ __forceinline__ void gemm_phase(LAS unsigned char* lds, const Gemm g, const Sched S, const Epi E, const int tid) {
;     ...
;             PG8_WAIT_V(8); PG8_WAIT_L(0); PG8_BAR; PG8_MMA(1, 0, At, B0); PG8_MMA(1, 1, At, B1); PG8_BAR; PG8_SCHED;
;             PG8_LDB(B0, 1, 0); PG8_LDB(B1, 1, 1); PG8_SCHED; PG8_LDA(At, 1, 0); PG8_STAGE(PG8_SA(0, 1), a2 + hstepA, voffA);
;             PG8_WAIT_V(8); PG8_WAIT_L(0); PG8_BAR; PG8_MMA(0, 0, At, B0); PG8_MMA(0, 1, At, B1); PG8_BAR; PG8_SCHED;
	s_setprio 1
	v_mfma_f32_16x16x32_bf16 v[94:97], v[98:101], v[200:203], v[94:97]
	v_mfma_f32_16x16x32_bf16 v[90:93], v[150:153], v[200:203], v[90:93]
	v_mfma_f32_16x16x32_bf16 v[86:89], v[98:101], v[208:211], v[86:89]
	v_mfma_f32_16x16x32_bf16 v[82:85], v[150:153], v[208:211], v[82:85]
	v_mfma_f32_16x16x32_bf16 v[78:81], v[98:101], v[216:219], v[78:81]
	v_mfma_f32_16x16x32_bf16 v[74:77], v[150:153], v[216:219], v[74:77]
	v_mfma_f32_16x16x32_bf16 v[70:73], v[98:101], v[224:227], v[70:73]
	v_mfma_f32_16x16x32_bf16 v[66:69], v[150:153], v[224:227], v[66:69]
	v_mfma_f32_16x16x32_bf16 v[94:97], v[102:105], v[204:207], v[94:97]
	v_mfma_f32_16x16x32_bf16 v[90:93], v[180:183], v[204:207], v[90:93]
	v_mfma_f32_16x16x32_bf16 v[86:89], v[102:105], v[212:215], v[86:89]
	v_mfma_f32_16x16x32_bf16 v[82:85], v[180:183], v[212:215], v[82:85]
	v_mfma_f32_16x16x32_bf16 v[78:81], v[102:105], v[220:223], v[78:81]
	v_mfma_f32_16x16x32_bf16 v[74:77], v[180:183], v[220:223], v[74:77]
	v_mfma_f32_16x16x32_bf16 v[70:73], v[102:105], v[228:231], v[70:73]
	v_mfma_f32_16x16x32_bf16 v[66:69], v[180:183], v[228:231], v[66:69]
	v_mfma_f32_16x16x32_bf16 v[30:33], v[184:187], v[200:203], v[30:33]
	v_mfma_f32_16x16x32_bf16 v[26:29], v[192:195], v[200:203], v[26:29]
	v_mfma_f32_16x16x32_bf16 v[22:25], v[184:187], v[208:211], v[22:25]
	v_mfma_f32_16x16x32_bf16 v[18:21], v[192:195], v[208:211], v[18:21]
	v_mfma_f32_16x16x32_bf16 v[14:17], v[184:187], v[216:219], v[14:17]
	v_mfma_f32_16x16x32_bf16 v[10:13], v[192:195], v[216:219], v[10:13]
	v_mfma_f32_16x16x32_bf16 v[6:9], v[184:187], v[224:227], v[6:9]
	v_mfma_f32_16x16x32_bf16 v[2:5], v[192:195], v[224:227], v[2:5]
	v_mfma_f32_16x16x32_bf16 v[30:33], v[188:191], v[204:207], v[30:33]
	v_mfma_f32_16x16x32_bf16 v[26:29], v[196:199], v[204:207], v[26:29]
	v_mfma_f32_16x16x32_bf16 v[22:25], v[188:191], v[212:215], v[22:25]
	v_mfma_f32_16x16x32_bf16 v[18:21], v[196:199], v[212:215], v[18:21]
	v_mfma_f32_16x16x32_bf16 v[14:17], v[188:191], v[220:223], v[14:17]
	v_mfma_f32_16x16x32_bf16 v[10:13], v[196:199], v[220:223], v[10:13]
	v_mfma_f32_16x16x32_bf16 v[6:9], v[188:191], v[228:231], v[6:9]
	v_mfma_f32_16x16x32_bf16 v[2:5], v[196:199], v[228:231], v[2:5]
	s_setprio 0
	s_barrier
	s_add_i32 s45, 0, 0x18000
	s_add_i32 s6, 0, 0x1c000
	v_add_u32_e32 v180, s45, v167
	v_add_u32_e32 v196, s6, v167
	ds_read_b128 v[98:101], v180
	ds_read_b128 v[102:105], v180 offset:1024
	ds_read_b128 v[150:153], v180 offset:2048
	ds_read_b128 v[180:183], v180 offset:3072
	ds_read_b128 v[184:187], v196
	ds_read_b128 v[188:191], v196 offset:1024
	ds_read_b128 v[192:195], v196 offset:2048
	ds_read_b128 v[196:199], v196 offset:3072
	s_add_u32 s10, s28, 0x40000
	s_addc_u32 s11, s29, 0
	s_mov_b32 m0, s49
	v_lshl_add_u64 v[248:249], s[10:11], 0, v[144:145]
	ds_read_b128 v[200:203], v179 offset:32768
	ds_read_b128 v[204:207], v179 offset:33792
	ds_read_b128 v[208:211], v179 offset:34816
	ds_read_b128 v[212:215], v179 offset:35840
	ds_read_b128 v[216:219], v179 offset:36864
	ds_read_b128 v[220:223], v179 offset:37888
	ds_read_b128 v[224:227], v179 offset:38912
	ds_read_b128 v[228:231], v179 offset:39936
	global_load_lds_dwordx4 v[248:249], off
	s_mov_b32 m0, s62
	v_lshl_add_u64 v[248:249], s[10:11], 0, v[140:141]
	global_load_lds_dwordx4 v[248:249], off
	s_waitcnt vmcnt(8)
	s_waitcnt lgkmcnt(0)
	s_barrier
	s_setprio 1
	v_mfma_f32_16x16x32_bf16 v[134:137], v[98:101], v[200:203], v[134:137]
	v_mfma_f32_16x16x32_bf16 v[130:133], v[150:153], v[200:203], v[130:133]
	v_mfma_f32_16x16x32_bf16 v[126:129], v[98:101], v[208:211], v[126:129]
	v_mfma_f32_16x16x32_bf16 v[122:125], v[150:153], v[208:211], v[122:125]
	v_mfma_f32_16x16x32_bf16 v[118:121], v[98:101], v[216:219], v[118:121]
	v_mfma_f32_16x16x32_bf16 v[114:117], v[150:153], v[216:219], v[114:117]
	v_mfma_f32_16x16x32_bf16 v[110:113], v[98:101], v[224:227], v[110:113]
	v_mfma_f32_16x16x32_bf16 v[106:109], v[150:153], v[224:227], v[106:109]
	v_mfma_f32_16x16x32_bf16 v[134:137], v[102:105], v[204:207], v[134:137]
	v_mfma_f32_16x16x32_bf16 v[130:133], v[180:183], v[204:207], v[130:133]
	v_mfma_f32_16x16x32_bf16 v[126:129], v[102:105], v[212:215], v[126:129]
	v_mfma_f32_16x16x32_bf16 v[122:125], v[180:183], v[212:215], v[122:125]
	v_mfma_f32_16x16x32_bf16 v[118:121], v[102:105], v[220:223], v[118:121]
	v_mfma_f32_16x16x32_bf16 v[114:117], v[180:183], v[220:223], v[114:117]
	v_mfma_f32_16x16x32_bf16 v[110:113], v[102:105], v[228:231], v[110:113]
	v_mfma_f32_16x16x32_bf16 v[106:109], v[180:183], v[228:231], v[106:109]
	v_mfma_f32_16x16x32_bf16 v[62:65], v[184:187], v[200:203], v[62:65]
	v_mfma_f32_16x16x32_bf16 v[58:61], v[192:195], v[200:203], v[58:61]
	v_mfma_f32_16x16x32_bf16 v[54:57], v[184:187], v[208:211], v[54:57]
	v_mfma_f32_16x16x32_bf16 v[50:53], v[192:195], v[208:211], v[50:53]
	v_mfma_f32_16x16x32_bf16 v[46:49], v[184:187], v[216:219], v[46:49]
	v_mfma_f32_16x16x32_bf16 v[42:45], v[192:195], v[216:219], v[42:45]
	v_mfma_f32_16x16x32_bf16 v[38:41], v[184:187], v[224:227], v[38:41]
	v_mfma_f32_16x16x32_bf16 v[34:37], v[192:195], v[224:227], v[34:37]
	v_mfma_f32_16x16x32_bf16 v[62:65], v[188:191], v[204:207], v[62:65]
	v_mfma_f32_16x16x32_bf16 v[58:61], v[196:199], v[204:207], v[58:61]
	v_mfma_f32_16x16x32_bf16 v[54:57], v[188:191], v[212:215], v[54:57]
	v_mfma_f32_16x16x32_bf16 v[50:53], v[196:199], v[212:215], v[50:53]
	v_mfma_f32_16x16x32_bf16 v[46:49], v[188:191], v[220:223], v[46:49]
	v_mfma_f32_16x16x32_bf16 v[42:45], v[196:199], v[220:223], v[42:45]
	v_mfma_f32_16x16x32_bf16 v[38:41], v[188:191], v[228:231], v[38:41]
	v_mfma_f32_16x16x32_bf16 v[34:37], v[196:199], v[228:231], v[34:37]
	s_setprio 0
	s_barrier
; #define PG8_STAGE(bufoff, gbase, voff) do { _Pragma("unroll") for (int _i = 0; _i < 2; ++_i) \
;         __builtin_amdgcn_global_load_lds((const unsigned*)((const char*)(gbase) + (voff)[_i]), (LAS unsigned*)(lds + (bufoff) + ldsw + _i * 8192), 16, 0, 0); } while (0)
; #define PG8_LDA(dst, b, h) do { _Pragma("unroll") for (int m = 0; m < 4; ++m) _Pragma("unroll") for (int k = 0; k < 2; ++k) dst[m][k] = *(const LAS bf16x8*)(lds + PG8_SA(b, h) + aoff + m * 2048 + k * 1024); } while (0)
; #define PG8_MMA(ai, bj, At, Bt) do { __builtin_amdgcn_s_setprio(1); _Pragma("unroll") for (int m = 0; m < 4; ++m) _Pragma("unroll") for (int n = 0; n < 2; ++n) _Pragma("unroll") for (int k = 0; k < 2; ++k) \
;         acc[ai][bj][m][n] = __builtin_amdgcn_mfma_f32_16x16x32_bf16(Bt[n][k], At[m][k], acc[ai][bj][m][n], 0, 0, 0); __builtin_amdgcn_s_setprio(0); } while (0)
; #define PG8_WAIT_V(n) asm volatile("s_waitcnt vmcnt(" #n ")" ::: "memory")
; #define PG8_WAIT_L(n) asm volatile("s_waitcnt lgkmcnt(" #n ")" ::: "memory")
; #define PG8_BAR __builtin_amdgcn_s_barrier()
; #define PG8_SCHED __builtin_amdgcn_sched_barrier(0)
; template <class Epi, class Sched>
; __device__ __forceinline__ void gemm_phase(LAS unsigned char* lds, const Gemm g, const Sched S, const Epi E, const int tid) {
;     ...
;             PG8_LDA(At, 1, 1); PG8_STAGE(PG8_SB(1, 0), b3, voffB); PG8_STAGE(PG8_SB(1, 1), b3 + hstepB, voffB); PG8_STAGE(PG8_SA(1, 0), a3, voffA);
;             PG8_WAIT_V(8); PG8_WAIT_L(0); PG8_BAR; PG8_MMA(1, 0, At, B0); PG8_MMA(1, 1, At, B1); PG8_BAR; PG8_SCHED;
;         }
;         if (wr == 0) PG8_BAR;
	s_add_i32 s7, s45, s46
	v_lshl_add_u64 v[154:155], v[154:155], 0, s[64:65]
	s_mov_b32 m0, s7
	ds_read_b128 v[200:203], v179 offset:49152
	ds_read_b128 v[204:207], v179 offset:50176
	ds_read_b128 v[208:211], v179 offset:51200
	ds_read_b128 v[212:215], v179 offset:52224
	ds_read_b128 v[216:219], v179 offset:53248
	ds_read_b128 v[220:223], v179 offset:54272
	ds_read_b128 v[224:227], v179 offset:55296
	ds_read_b128 v[228:231], v179 offset:56320
	global_load_lds_dwordx4 v[154:155], off
	s_add_i32 m0, s7, 0x2000
	s_add_u32 s10, s26, 0x80080
	v_lshl_add_u64 v[154:155], v[232:233], 0, s[64:65]
	s_addc_u32 s11, s27, 0
	s_add_i32 s6, s6, s46
	global_load_lds_dwordx4 v[154:155], off
	s_mov_b32 m0, s6
	v_lshl_add_u64 v[154:155], s[10:11], 0, v[142:143]
	global_load_lds_dwordx4 v[154:155], off
	s_add_i32 m0, s6, 0x2000
	v_lshl_add_u64 v[154:155], s[10:11], 0, v[138:139]
	global_load_lds_dwordx4 v[154:155], off
	s_mov_b32 m0, s84
	v_lshl_add_u64 v[154:155], v[234:235], 0, s[64:65]
	global_load_lds_dwordx4 v[154:155], off
	s_mov_b32 m0, s85
	v_lshl_add_u64 v[154:155], v[246:247], 0, s[64:65]
	global_load_lds_dwordx4 v[154:155], off
	s_waitcnt vmcnt(8)
	s_waitcnt lgkmcnt(0)
	s_barrier
	s_setprio 1
	v_mfma_f32_16x16x32_bf16 v[94:97], v[98:101], v[200:203], v[94:97]
	v_mfma_f32_16x16x32_bf16 v[90:93], v[150:153], v[200:203], v[90:93]
	v_mfma_f32_16x16x32_bf16 v[86:89], v[98:101], v[208:211], v[86:89]
	v_mfma_f32_16x16x32_bf16 v[82:85], v[150:153], v[208:211], v[82:85]
	v_mfma_f32_16x16x32_bf16 v[78:81], v[98:101], v[216:219], v[78:81]
	v_mfma_f32_16x16x32_bf16 v[74:77], v[150:153], v[216:219], v[74:77]
	v_mfma_f32_16x16x32_bf16 v[70:73], v[98:101], v[224:227], v[70:73]
	v_mfma_f32_16x16x32_bf16 v[66:69], v[150:153], v[224:227], v[66:69]
	v_mfma_f32_16x16x32_bf16 v[94:97], v[102:105], v[204:207], v[94:97]
	v_mfma_f32_16x16x32_bf16 v[90:93], v[180:183], v[204:207], v[90:93]
	v_mfma_f32_16x16x32_bf16 v[86:89], v[102:105], v[212:215], v[86:89]
	v_mfma_f32_16x16x32_bf16 v[82:85], v[180:183], v[212:215], v[82:85]
	v_mfma_f32_16x16x32_bf16 v[78:81], v[102:105], v[220:223], v[78:81]
	v_mfma_f32_16x16x32_bf16 v[74:77], v[180:183], v[220:223], v[74:77]
	v_mfma_f32_16x16x32_bf16 v[70:73], v[102:105], v[228:231], v[70:73]
	v_mfma_f32_16x16x32_bf16 v[66:69], v[180:183], v[228:231], v[66:69]
	v_mfma_f32_16x16x32_bf16 v[30:33], v[184:187], v[200:203], v[30:33]
	v_mfma_f32_16x16x32_bf16 v[26:29], v[192:195], v[200:203], v[26:29]
	v_mfma_f32_16x16x32_bf16 v[22:25], v[184:187], v[208:211], v[22:25]
	v_mfma_f32_16x16x32_bf16 v[18:21], v[192:195], v[208:211], v[18:21]
	v_mfma_f32_16x16x32_bf16 v[14:17], v[184:187], v[216:219], v[14:17]
	v_mfma_f32_16x16x32_bf16 v[10:13], v[192:195], v[216:219], v[10:13]
	v_mfma_f32_16x16x32_bf16 v[6:9], v[184:187], v[224:227], v[6:9]
	v_mfma_f32_16x16x32_bf16 v[2:5], v[192:195], v[224:227], v[2:5]
	v_mfma_f32_16x16x32_bf16 v[30:33], v[188:191], v[204:207], v[30:33]
	v_mfma_f32_16x16x32_bf16 v[26:29], v[196:199], v[204:207], v[26:29]
	v_mfma_f32_16x16x32_bf16 v[22:25], v[188:191], v[212:215], v[22:25]
	v_mfma_f32_16x16x32_bf16 v[18:21], v[196:199], v[212:215], v[18:21]
	v_mfma_f32_16x16x32_bf16 v[14:17], v[188:191], v[220:223], v[14:17]
	v_mfma_f32_16x16x32_bf16 v[10:13], v[196:199], v[220:223], v[10:13]
	v_mfma_f32_16x16x32_bf16 v[6:9], v[188:191], v[228:231], v[6:9]
	v_mfma_f32_16x16x32_bf16 v[2:5], v[196:199], v[228:231], v[2:5]
	s_setprio 0
	s_barrier
	s_add_i32 vcc_hi, vcc_hi, 2
	s_add_u32 s97, s97, 0x100
	s_addc_u32 vcc_lo, vcc_lo, 0
	s_add_u32 s22, s22, 0x100
	s_addc_u32 s23, s23, 0
	s_cmp_gt_u32 vcc_hi, 29
	s_cbranch_scc0 .LBB0_299
	s_and_b64 vcc, exec, s[18:19]
	s_cbranch_vccz .LBB0_302
	s_barrier

;     __host__ __device__ bool next(int i, Unit& u) const { const int L = i * G + c; if (L >= 32) return false; u.pm = L; u.pn = L >> 4; return true; }
; #define PG8_STAGE(bufoff, gbase, voff) do { _Pragma("unroll") for (int _i = 0; _i < 2; ++_i) \
;         __builtin_amdgcn_global_load_lds((const unsigned*)((const char*)(gbase) + (voff)[_i]), (LAS unsigned*)(lds + (bufoff) + ldsw + _i * 8192), 16, 0, 0); } while (0)
; #define PG8_LDA(dst, b, h) do { _Pragma("unroll") for (int m = 0; m < 4; ++m) _Pragma("unroll") for (int k = 0; k < 2; ++k) dst[m][k] = *(const LAS bf16x8*)(lds + PG8_SA(b, h) + aoff + m * 2048 + k * 1024); } while (0)
; #define PG8_LDB(dst, b, h) do { _Pragma("unroll") for (int n = 0; n < 2; ++n) _Pragma("unroll") for (int k = 0; k < 2; ++k) dst[n][k] = *(const LAS bf16x8*)(lds + PG8_SB(b, h) + boff + n * 2048 + k * 1024); } while (0)
; #define PG8_WAIT_V(n) asm volatile("s_waitcnt vmcnt(" #n ")" ::: "memory")
; #define PG8_WAIT_L(n) asm volatile("s_waitcnt lgkmcnt(" #n ")" ::: "memory")
; #define PG8_BAR __builtin_amdgcn_s_barrier()
; #define PG8_SCHED __builtin_amdgcn_sched_barrier(0)
; template <class Epi, class Sched>
; __device__ __forceinline__ void gemm_phase(LAS unsigned char* lds, const Gemm g, const Sched S, const Epi E, const int tid) {
;     ...
;         const bool has_next = S.next(ui + 1, nxt);
;         const char* nA = has_next ? (const char*)g.A + (size_t)nxt.pm * tstepA : cA; const char* nB = has_next ? (const char*)g.Bt + (size_t)nxt.pn * tstepB : cB;
;         for (int t = 0; t < nt; t += 2) {
;             const bool last = (t == nt - 2);
;             const char* a1 = cA + (size_t)(t + 1) * kstep;
;             const char* a2 = last ? nA : cA + (size_t)(t + 2) * kstep; const char* b2 = last ? nB : cB + (size_t)(t + 2) * kstep;
;             const char* a3 = a2 + kstep; const char* b3 = b2 + kstep;
;             PG8_LDB(B0, 0, 0); PG8_LDB(B1, 0, 1); PG8_SCHED; PG8_LDA(At, 0, 0); PG8_STAGE(PG8_SA(1, 1), a1 + hstepA, voffA);
;             PG8_WAIT_V(8); PG8_WAIT_L(0); PG8_BAR; PG8_MMA(0, 0, At, B0); PG8_MMA(0, 1, At, B1); PG8_BAR; PG8_SCHED;
;             PG8_LDA(At, 0, 1); PG8_STAGE(PG8_SB(0, 0), b2, voffB); PG8_STAGE(PG8_SB(0, 1), b2 + hstepB, voffB); PG8_STAGE(PG8_SA(0, 0), a2, voffA);
;             PG8_WAIT_V(8); PG8_WAIT_L(0); PG8_BAR; PG8_MMA(1, 0, At, B0); PG8_MMA(1, 1, At, B1); PG8_BAR; PG8_SCHED;
.LBB0_310:
	s_mov_b32 s6, s92
	s_ashr_i32 s92, s89, 4
	s_cmp_lt_i32 s89, 32
	s_mov_b64 s[42:43], s[4:5]
	s_cselect_b64 s[4:5], -1, 0
	s_and_b64 s[4:5], s[4:5], exec
	s_cselect_b32 s4, s92, s6
	s_ashr_i32 s5, s4, 31
	s_lshl_b64 s[4:5], s[4:5], 17
	s_add_u32 s4, s25, s4
	s_addc_u32 s5, s46, s5
	s_cmp_lt_i32 s89, 32
	s_cselect_b64 s[10:11], -1, 0
	s_and_b64 s[10:11], s[10:11], exec
	s_cselect_b32 s10, s89, s93
	v_add_u32_e32 v130, s44, v70
	s_cselect_b32 s26, s4, s42
	s_cselect_b32 s27, s5, s43
	s_ashr_i32 s11, s10, 31
	ds_read_b128 v[2:5], v130
	ds_read_b128 v[6:9], v130 offset:1024
	ds_read_b128 v[10:13], v130 offset:2048
	ds_read_b128 v[14:17], v130 offset:3072
	s_lshl_b64 s[10:11], s[10:11], 17
	s_mov_b64 s[40:41], s[16:17]
	s_add_u32 s16, s8, s10
	s_addc_u32 s17, s9, s11
	s_cmp_lt_i32 s89, 32
	s_cselect_b64 s[22:23], -1, 0
	s_and_b64 s[10:11], s[22:23], exec
	s_cselect_b32 s29, s17, s41
	s_cselect_b32 s28, s16, s40
	s_add_u32 s10, s40, 0x10080
	s_addc_u32 s11, s41, 0
	s_add_i32 s97, s37, 0xc000
	v_lshl_add_u64 v[50:51], s[10:11], 0, v[68:69]
	s_mov_b32 m0, s97
	s_add_i32 s13, s37, 0xe000
	ds_read_b128 v[18:21], v71
	ds_read_b128 v[22:25], v71 offset:1024
	ds_read_b128 v[26:29], v71 offset:2048
	ds_read_b128 v[30:33], v71 offset:3072
	ds_read_b128 v[34:37], v71 offset:4096
	ds_read_b128 v[38:41], v71 offset:5120
	ds_read_b128 v[42:45], v71 offset:6144
	ds_read_b128 v[46:49], v71 offset:7168
	global_load_lds_dwordx4 v[50:51], off
	s_mov_b32 m0, s13
	v_lshl_add_u64 v[50:51], s[10:11], 0, v[66:67]
	global_load_lds_dwordx4 v[50:51], off
	s_waitcnt vmcnt(8)
	s_waitcnt lgkmcnt(0)
	s_barrier
	s_setprio 1
	v_mfma_f32_16x16x32_bf16 v[50:53], v[2:5], v[18:21], 0
	v_mfma_f32_16x16x32_bf16 v[18:21], v[10:13], v[18:21], 0
	v_mfma_f32_16x16x32_bf16 v[50:53], v[6:9], v[22:25], v[50:53]
	v_mfma_f32_16x16x32_bf16 v[18:21], v[14:17], v[22:25], v[18:21]
	v_mfma_f32_16x16x32_bf16 v[22:25], v[2:5], v[26:29], 0
	v_mfma_f32_16x16x32_bf16 v[26:29], v[10:13], v[26:29], 0
	v_mfma_f32_16x16x32_bf16 v[22:25], v[6:9], v[30:33], v[22:25]
	v_mfma_f32_16x16x32_bf16 v[26:29], v[14:17], v[30:33], v[26:29]
	v_mfma_f32_16x16x32_bf16 v[30:33], v[2:5], v[34:37], 0
	v_mfma_f32_16x16x32_bf16 v[34:37], v[10:13], v[34:37], 0
	v_mfma_f32_16x16x32_bf16 v[30:33], v[6:9], v[38:41], v[30:33]
	v_mfma_f32_16x16x32_bf16 v[34:37], v[14:17], v[38:41], v[34:37]
	v_mfma_f32_16x16x32_bf16 v[38:41], v[2:5], v[42:45], 0
	v_mfma_f32_16x16x32_bf16 v[42:45], v[10:13], v[42:45], 0
	v_mfma_f32_16x16x32_bf16 v[38:41], v[6:9], v[46:49], v[38:41]
	v_mfma_f32_16x16x32_bf16 v[42:45], v[14:17], v[46:49], v[42:45]
	s_setprio 0
	s_barrier
	s_add_i32 s96, s44, s47
	v_lshl_add_u64 v[120:121], s[42:43], 0, v[68:69]
	s_mov_b64 s[6:7], 0x100
	s_add_i32 s94, s96, 0x2000
	v_lshl_add_u64 v[88:89], v[120:121], 0, s[6:7]
	s_mov_b32 m0, s96
	v_lshl_add_u64 v[122:123], s[42:43], 0, v[66:67]
	s_add_u32 s10, s42, 0x10100
	ds_read_b128 v[46:49], v71 offset:16384
	ds_read_b128 v[54:57], v71 offset:17408
	ds_read_b128 v[58:61], v71 offset:18432
	ds_read_b128 v[62:65], v71 offset:19456
	ds_read_b128 v[72:75], v71 offset:20480
	ds_read_b128 v[76:79], v71 offset:21504
	ds_read_b128 v[80:83], v71 offset:22528
	ds_read_b128 v[84:87], v71 offset:23552
	global_load_lds_dwordx4 v[88:89], off
	v_lshl_add_u64 v[88:89], v[122:123], 0, s[6:7]
	s_mov_b32 m0, s94
	s_addc_u32 s11, s43, 0
	global_load_lds_dwordx4 v[88:89], off
	v_lshl_add_u64 v[88:89], s[10:11], 0, v[68:69]
	s_mov_b32 m0, s48
	v_lshl_add_u64 v[124:125], s[40:41], 0, v[68:69]
	global_load_lds_dwordx4 v[88:89], off
	v_lshl_add_u64 v[88:89], s[10:11], 0, v[66:67]
	s_mov_b32 m0, s49
	v_lshl_add_u64 v[126:127], s[40:41], 0, v[66:67]
	global_load_lds_dwordx4 v[88:89], off
	s_mov_b32 m0, s37
	v_lshl_add_u64 v[88:89], v[124:125], 0, s[6:7]
	global_load_lds_dwordx4 v[88:89], off
	s_mov_b32 m0, s62
	v_lshl_add_u64 v[88:89], v[126:127], 0, s[6:7]
	global_load_lds_dwordx4 v[88:89], off
	s_waitcnt vmcnt(8)
	s_waitcnt lgkmcnt(0)
	s_barrier
	s_setprio 1
	v_mfma_f32_16x16x32_bf16 v[88:91], v[2:5], v[46:49], 0
	v_mfma_f32_16x16x32_bf16 v[46:49], v[10:13], v[46:49], 0
	v_mfma_f32_16x16x32_bf16 v[88:91], v[6:9], v[54:57], v[88:91]
	v_mfma_f32_16x16x32_bf16 v[46:49], v[14:17], v[54:57], v[46:49]
	v_mfma_f32_16x16x32_bf16 v[54:57], v[2:5], v[58:61], 0
	v_mfma_f32_16x16x32_bf16 v[58:61], v[10:13], v[58:61], 0
	v_mfma_f32_16x16x32_bf16 v[54:57], v[6:9], v[62:65], v[54:57]
	v_mfma_f32_16x16x32_bf16 v[58:61], v[14:17], v[62:65], v[58:61]
	v_mfma_f32_16x16x32_bf16 v[62:65], v[2:5], v[72:75], 0
	v_mfma_f32_16x16x32_bf16 v[2:5], v[2:5], v[80:83], 0
	v_mfma_f32_16x16x32_bf16 v[62:65], v[6:9], v[76:79], v[62:65]
	v_mfma_f32_16x16x32_bf16 v[2:5], v[6:9], v[84:87], v[2:5]
	v_mfma_f32_16x16x32_bf16 v[6:9], v[10:13], v[80:83], 0
	v_mfma_f32_16x16x32_bf16 v[72:75], v[10:13], v[72:75], 0
	v_mfma_f32_16x16x32_bf16 v[6:9], v[14:17], v[84:87], v[6:9]
	v_mfma_f32_16x16x32_bf16 v[72:75], v[14:17], v[76:79], v[72:75]
	s_setprio 0
	s_barrier
	v_add_u32_e32 v131, s45, v70
	ds_read_b128 v[10:13], v131
	ds_read_b128 v[14:17], v131 offset:1024
	ds_read_b128 v[76:79], v131 offset:2048
	ds_read_b128 v[80:83], v131 offset:3072
	s_add_u32 s10, s40, 0x10100
	s_addc_u32 s11, s41, 0
	s_mov_b32 m0, s68
	v_lshl_add_u64 v[128:129], s[10:11], 0, v[68:69]
	ds_read_b128 v[84:87], v71 offset:32768
	ds_read_b128 v[92:95], v71 offset:33792
	ds_read_b128 v[96:99], v71 offset:34816
	ds_read_b128 v[100:103], v71 offset:35840
	ds_read_b128 v[104:107], v71 offset:36864
	ds_read_b128 v[108:111], v71 offset:37888
	ds_read_b128 v[112:115], v71 offset:38912
	ds_read_b128 v[116:119], v71 offset:39936
	global_load_lds_dwordx4 v[128:129], off
	s_mov_b32 m0, s69
	v_lshl_add_u64 v[128:129], s[10:11], 0, v[66:67]
	global_load_lds_dwordx4 v[128:129], off
	s_waitcnt vmcnt(8)
	s_waitcnt lgkmcnt(0)
	s_barrier
; #define PG8_STAGE(bufoff, gbase, voff) do { _Pragma("unroll") for (int _i = 0; _i < 2; ++_i) \
;         __builtin_amdgcn_global_load_lds((const unsigned*)((const char*)(gbase) + (voff)[_i]), (LAS unsigned*)(lds + (bufoff) + ldsw + _i * 8192), 16, 0, 0); } while (0)
; #define PG8_LDA(dst, b, h) do { _Pragma("unroll") for (int m = 0; m < 4; ++m) _Pragma("unroll") for (int k = 0; k < 2; ++k) dst[m][k] = *(const LAS bf16x8*)(lds + PG8_SA(b, h) + aoff + m * 2048 + k * 1024); } while (0)
; #define PG8_LDB(dst, b, h) do { _Pragma("unroll") for (int n = 0; n < 2; ++n) _Pragma("unroll") for (int k = 0; k < 2; ++k) dst[n][k] = *(const LAS bf16x8*)(lds + PG8_SB(b, h) + boff + n * 2048 + k * 1024); } while (0)
; #define PG8_MMA(ai, bj, At, Bt) do { __builtin_amdgcn_s_setprio(1); _Pragma("unroll") for (int m = 0; m < 4; ++m) _Pragma("unroll") for (int n = 0; n < 2; ++n) _Pragma("unroll") for (int k = 0; k < 2; ++k) \
;         acc[ai][bj][m][n] = __builtin_amdgcn_mfma_f32_16x16x32_bf16(Bt[n][k], At[m][k], acc[ai][bj][m][n], 0, 0, 0); __builtin_amdgcn_s_setprio(0); } while (0)
; #define PG8_WAIT_V(n) asm volatile("s_waitcnt vmcnt(" #n ")" ::: "memory")
; #define PG8_WAIT_L(n) asm volatile("s_waitcnt lgkmcnt(" #n ")" ::: "memory")
; #define PG8_BAR __builtin_amdgcn_s_barrier()
; #define PG8_SCHED __builtin_amdgcn_sched_barrier(0)
; template <class Epi, class Sched>
; __device__ __forceinline__ void gemm_phase(LAS unsigned char* lds, const Gemm g, const Sched S, const Epi E, const int tid) {
;     ...
;             PG8_WAIT_V(8); PG8_WAIT_L(0); PG8_BAR; PG8_MMA(1, 0, At, B0); PG8_MMA(1, 1, At, B1); PG8_BAR; PG8_SCHED;
;             PG8_LDB(B0, 1, 0); PG8_LDB(B1, 1, 1); PG8_SCHED; PG8_LDA(At, 1, 0); PG8_STAGE(PG8_SA(0, 1), a2 + hstepA, voffA);
;             PG8_WAIT_V(8); PG8_WAIT_L(0); PG8_BAR; PG8_MMA(0, 0, At, B0); PG8_MMA(0, 1, At, B1); PG8_BAR; PG8_SCHED;
;             PG8_LDA(At, 1, 1); PG8_STAGE(PG8_SB(1, 0), b3, voffB); PG8_STAGE(PG8_SB(1, 1), b3 + hstepB, voffB); PG8_STAGE(PG8_SA(1, 0), a3, voffA);
;             PG8_WAIT_V(8); PG8_WAIT_L(0); PG8_BAR; PG8_MMA(1, 0, At, B0); PG8_MMA(1, 1, At, B1); PG8_BAR; PG8_SCHED;
	s_setprio 1
	v_mfma_f32_16x16x32_bf16 v[50:53], v[10:13], v[84:87], v[50:53]
	v_mfma_f32_16x16x32_bf16 v[18:21], v[76:79], v[84:87], v[18:21]
	v_mfma_f32_16x16x32_bf16 v[22:25], v[10:13], v[96:99], v[22:25]
	v_mfma_f32_16x16x32_bf16 v[26:29], v[76:79], v[96:99], v[26:29]
	v_mfma_f32_16x16x32_bf16 v[30:33], v[10:13], v[104:107], v[30:33]
	v_mfma_f32_16x16x32_bf16 v[34:37], v[76:79], v[104:107], v[34:37]
	v_mfma_f32_16x16x32_bf16 v[38:41], v[10:13], v[112:115], v[38:41]
	v_mfma_f32_16x16x32_bf16 v[42:45], v[76:79], v[112:115], v[42:45]
	v_mfma_f32_16x16x32_bf16 v[50:53], v[14:17], v[92:95], v[50:53]
	v_mfma_f32_16x16x32_bf16 v[18:21], v[80:83], v[92:95], v[18:21]
	v_mfma_f32_16x16x32_bf16 v[22:25], v[14:17], v[100:103], v[22:25]
	v_mfma_f32_16x16x32_bf16 v[26:29], v[80:83], v[100:103], v[26:29]
	v_mfma_f32_16x16x32_bf16 v[30:33], v[14:17], v[108:111], v[30:33]
	v_mfma_f32_16x16x32_bf16 v[34:37], v[80:83], v[108:111], v[34:37]
	v_mfma_f32_16x16x32_bf16 v[38:41], v[14:17], v[116:119], v[38:41]
	v_mfma_f32_16x16x32_bf16 v[42:45], v[80:83], v[116:119], v[42:45]
	s_setprio 0
	s_barrier
	s_add_i32 vcc_lo, s45, s47
	s_mov_b64 s[6:7], 0x180
	s_add_i32 s95, vcc_lo, 0x2000
	v_lshl_add_u64 v[120:121], v[120:121], 0, s[6:7]
	s_mov_b32 m0, vcc_lo
	s_add_u32 s10, s42, 0x10180
	ds_read_b128 v[84:87], v71 offset:49152
	ds_read_b128 v[92:95], v71 offset:50176
	ds_read_b128 v[96:99], v71 offset:51200
	ds_read_b128 v[100:103], v71 offset:52224
	ds_read_b128 v[104:107], v71 offset:53248
	ds_read_b128 v[108:111], v71 offset:54272
	ds_read_b128 v[112:115], v71 offset:55296
	ds_read_b128 v[116:119], v71 offset:56320
	global_load_lds_dwordx4 v[120:121], off
	v_lshl_add_u64 v[120:121], v[122:123], 0, s[6:7]
	s_mov_b32 m0, s95
	s_addc_u32 s11, s43, 0
	global_load_lds_dwordx4 v[120:121], off
	s_mov_b32 m0, s85
	v_lshl_add_u64 v[120:121], s[10:11], 0, v[68:69]
	global_load_lds_dwordx4 v[120:121], off
	s_mov_b32 m0, s88
	v_lshl_add_u64 v[120:121], s[10:11], 0, v[66:67]
	global_load_lds_dwordx4 v[120:121], off
	s_mov_b32 m0, s83
	v_lshl_add_u64 v[120:121], v[124:125], 0, s[6:7]
	global_load_lds_dwordx4 v[120:121], off
	s_mov_b32 m0, s84
	v_lshl_add_u64 v[120:121], v[126:127], 0, s[6:7]
	global_load_lds_dwordx4 v[120:121], off
	s_waitcnt vmcnt(8)
	s_waitcnt lgkmcnt(0)
	s_barrier
	s_setprio 1
	v_mfma_f32_16x16x32_bf16 v[46:49], v[76:79], v[84:87], v[46:49]
	v_mfma_f32_16x16x32_bf16 v[54:57], v[10:13], v[96:99], v[54:57]
	v_mfma_f32_16x16x32_bf16 v[58:61], v[76:79], v[96:99], v[58:61]
	v_mfma_f32_16x16x32_bf16 v[62:65], v[10:13], v[104:107], v[62:65]
	v_mfma_f32_16x16x32_bf16 v[2:5], v[10:13], v[112:115], v[2:5]
	v_mfma_f32_16x16x32_bf16 v[6:9], v[76:79], v[112:115], v[6:9]
	v_mfma_f32_16x16x32_bf16 v[88:91], v[10:13], v[84:87], v[88:91]
	v_mfma_f32_16x16x32_bf16 v[46:49], v[80:83], v[92:95], v[46:49]
	v_mfma_f32_16x16x32_bf16 v[54:57], v[14:17], v[100:103], v[54:57]
	v_mfma_f32_16x16x32_bf16 v[58:61], v[80:83], v[100:103], v[58:61]
	v_mfma_f32_16x16x32_bf16 v[62:65], v[14:17], v[108:111], v[62:65]
	v_mfma_f32_16x16x32_bf16 v[72:75], v[76:79], v[104:107], v[72:75]
	v_mfma_f32_16x16x32_bf16 v[2:5], v[14:17], v[116:119], v[2:5]
	v_mfma_f32_16x16x32_bf16 v[6:9], v[80:83], v[116:119], v[6:9]
	v_mfma_f32_16x16x32_bf16 v[88:91], v[14:17], v[92:95], v[88:91]
	v_mfma_f32_16x16x32_bf16 v[72:75], v[80:83], v[108:111], v[72:75]
	s_setprio 0
	s_barrier
	ds_read_b128 v[10:13], v130
	ds_read_b128 v[14:17], v130 offset:1024
	ds_read_b128 v[76:79], v130 offset:2048
	ds_read_b128 v[80:83], v130 offset:3072
	s_add_u32 s10, s40, 0x10180
	s_addc_u32 s11, s41, 0
	s_mov_b32 m0, s97
	v_lshl_add_u64 v[120:121], s[10:11], 0, v[68:69]
	ds_read_b128 v[84:87], v71
	ds_read_b128 v[92:95], v71 offset:1024
	ds_read_b128 v[96:99], v71 offset:2048
	ds_read_b128 v[100:103], v71 offset:3072
	ds_read_b128 v[104:107], v71 offset:4096
	ds_read_b128 v[108:111], v71 offset:5120
	ds_read_b128 v[112:115], v71 offset:6144
	ds_read_b128 v[116:119], v71 offset:7168
	global_load_lds_dwordx4 v[120:121], off
	s_mov_b32 m0, s13
	v_lshl_add_u64 v[120:121], s[10:11], 0, v[66:67]
	global_load_lds_dwordx4 v[120:121], off
	s_waitcnt vmcnt(8)
	s_waitcnt lgkmcnt(0)
	s_barrier
	s_setprio 1
	v_mfma_f32_16x16x32_bf16 v[38:41], v[10:13], v[112:115], v[38:41]
	v_mfma_f32_16x16x32_bf16 v[50:53], v[10:13], v[84:87], v[50:53]
	v_mfma_f32_16x16x32_bf16 v[18:21], v[76:79], v[84:87], v[18:21]
	v_mfma_f32_16x16x32_bf16 v[22:25], v[10:13], v[96:99], v[22:25]
	v_mfma_f32_16x16x32_bf16 v[26:29], v[76:79], v[96:99], v[26:29]
	v_mfma_f32_16x16x32_bf16 v[30:33], v[10:13], v[104:107], v[30:33]
	v_mfma_f32_16x16x32_bf16 v[34:37], v[76:79], v[104:107], v[34:37]
	v_mfma_f32_16x16x32_bf16 v[84:87], v[14:17], v[116:119], v[38:41]
	v_mfma_f32_16x16x32_bf16 v[38:41], v[76:79], v[112:115], v[42:45]
	v_mfma_f32_16x16x32_bf16 v[50:53], v[14:17], v[92:95], v[50:53]
	v_mfma_f32_16x16x32_bf16 v[18:21], v[80:83], v[92:95], v[18:21]
	v_mfma_f32_16x16x32_bf16 v[22:25], v[14:17], v[100:103], v[22:25]
	v_mfma_f32_16x16x32_bf16 v[26:29], v[80:83], v[100:103], v[26:29]
	v_mfma_f32_16x16x32_bf16 v[30:33], v[14:17], v[108:111], v[30:33]
	v_mfma_f32_16x16x32_bf16 v[34:37], v[80:83], v[108:111], v[34:37]
	v_mfma_f32_16x16x32_bf16 v[42:45], v[80:83], v[116:119], v[38:41]
	s_setprio 0
	s_barrier
; #define PG8_STAGE(bufoff, gbase, voff) do { _Pragma("unroll") for (int _i = 0; _i < 2; ++_i) \
;         __builtin_amdgcn_global_load_lds((const unsigned*)((const char*)(gbase) + (voff)[_i]), (LAS unsigned*)(lds + (bufoff) + ldsw + _i * 8192), 16, 0, 0); } while (0)
; #define PG8_LDA(dst, b, h) do { _Pragma("unroll") for (int m = 0; m < 4; ++m) _Pragma("unroll") for (int k = 0; k < 2; ++k) dst[m][k] = *(const LAS bf16x8*)(lds + PG8_SA(b, h) + aoff + m * 2048 + k * 1024); } while (0)
; #define PG8_MMA(ai, bj, At, Bt) do { __builtin_amdgcn_s_setprio(1); _Pragma("unroll") for (int m = 0; m < 4; ++m) _Pragma("unroll") for (int n = 0; n < 2; ++n) _Pragma("unroll") for (int k = 0; k < 2; ++k) \
;         acc[ai][bj][m][n] = __builtin_amdgcn_mfma_f32_16x16x32_bf16(Bt[n][k], At[m][k], acc[ai][bj][m][n], 0, 0, 0); __builtin_amdgcn_s_setprio(0); } while (0)
; #define PG8_WAIT_V(n) asm volatile("s_waitcnt vmcnt(" #n ")" ::: "memory")
; #define PG8_WAIT_L(n) asm volatile("s_waitcnt lgkmcnt(" #n ")" ::: "memory")
; #define PG8_BAR __builtin_amdgcn_s_barrier()
; #define PG8_SCHED __builtin_amdgcn_sched_barrier(0)
; template <class Epi, class Sched>
; __device__ __forceinline__ void gemm_phase(LAS unsigned char* lds, const Gemm g, const Sched S, const Epi E, const int tid) {
;     ...
;             PG8_WAIT_V(8); PG8_WAIT_L(0); PG8_BAR; PG8_MMA(0, 0, At, B0); PG8_MMA(0, 1, At, B1); PG8_BAR; PG8_SCHED;
;             PG8_LDA(At, 1, 1); PG8_STAGE(PG8_SB(1, 0), b3, voffB); PG8_STAGE(PG8_SB(1, 1), b3 + hstepB, voffB); PG8_STAGE(PG8_SA(1, 0), a3, voffA);
;             PG8_WAIT_V(8); PG8_WAIT_L(0); PG8_BAR; PG8_MMA(1, 0, At, B0); PG8_MMA(1, 1, At, B1); PG8_BAR; PG8_SCHED;
;         }
;         if (wr == 0) PG8_BAR;
	s_mov_b32 m0, s96
	v_lshl_add_u64 v[132:133], s[26:27], 0, v[68:69]
	s_add_u32 s10, s26, 0x10000
	ds_read_b128 v[38:41], v71 offset:16384
	ds_read_b128 v[92:95], v71 offset:17408
	ds_read_b128 v[96:99], v71 offset:18432
	ds_read_b128 v[100:103], v71 offset:19456
	ds_read_b128 v[104:107], v71 offset:20480
	ds_read_b128 v[108:111], v71 offset:21504
	ds_read_b128 v[112:115], v71 offset:22528
	ds_read_b128 v[116:119], v71 offset:23552
	global_load_lds_dwordx4 v[132:133], off
	v_lshl_add_u64 v[134:135], s[26:27], 0, v[66:67]
	s_mov_b32 m0, s94
	s_addc_u32 s11, s27, 0
	global_load_lds_dwordx4 v[134:135], off
	v_lshl_add_u64 v[120:121], s[10:11], 0, v[68:69]
	s_mov_b32 m0, s48
	v_lshl_add_u64 v[136:137], s[28:29], 0, v[68:69]
	global_load_lds_dwordx4 v[120:121], off
	v_lshl_add_u64 v[120:121], s[10:11], 0, v[66:67]
	s_mov_b32 m0, s49
	v_lshl_add_u64 v[138:139], s[28:29], 0, v[66:67]
	global_load_lds_dwordx4 v[120:121], off
	s_mov_b32 m0, s37
	s_nop 0
	global_load_lds_dwordx4 v[136:137], off
	s_mov_b32 m0, s62
	s_nop 0
	global_load_lds_dwordx4 v[138:139], off
	s_waitcnt vmcnt(8)
	s_waitcnt lgkmcnt(0)
	s_barrier
	s_setprio 1
	v_mfma_f32_16x16x32_bf16 v[88:91], v[10:13], v[38:41], v[88:91]
	v_mfma_f32_16x16x32_bf16 v[38:41], v[76:79], v[38:41], v[46:49]
	v_mfma_f32_16x16x32_bf16 v[88:91], v[14:17], v[92:95], v[88:91]
	v_mfma_f32_16x16x32_bf16 v[92:95], v[80:83], v[92:95], v[38:41]
	v_mfma_f32_16x16x32_bf16 v[38:41], v[10:13], v[96:99], v[54:57]
	v_mfma_f32_16x16x32_bf16 v[120:123], v[14:17], v[100:103], v[38:41]
	v_mfma_f32_16x16x32_bf16 v[38:41], v[76:79], v[96:99], v[58:61]
	v_mfma_f32_16x16x32_bf16 v[96:99], v[80:83], v[100:103], v[38:41]
	v_mfma_f32_16x16x32_bf16 v[38:41], v[10:13], v[104:107], v[62:65]
	v_mfma_f32_16x16x32_bf16 v[2:5], v[10:13], v[112:115], v[2:5]
	v_mfma_f32_16x16x32_bf16 v[100:103], v[14:17], v[108:111], v[38:41]
	v_mfma_f32_16x16x32_bf16 v[38:41], v[76:79], v[104:107], v[72:75]
	v_mfma_f32_16x16x32_bf16 v[2:5], v[14:17], v[116:119], v[2:5]
	v_mfma_f32_16x16x32_bf16 v[6:9], v[76:79], v[112:115], v[6:9]
	v_mfma_f32_16x16x32_bf16 v[72:75], v[80:83], v[108:111], v[38:41]
	v_mfma_f32_16x16x32_bf16 v[76:79], v[80:83], v[116:119], v[6:9]
	s_setprio 0
	s_barrier
	s_nop 1
	ds_read_b128 v[6:9], v131
	ds_read_b128 v[80:83], v131 offset:1024
	ds_read_b128 v[104:107], v131 offset:2048
	ds_read_b128 v[108:111], v131 offset:3072
	s_add_u32 s10, s28, 0x10000
	s_addc_u32 s11, s29, 0
	s_mov_b32 m0, s68
	v_lshl_add_u64 v[54:55], s[10:11], 0, v[68:69]
	ds_read_b128 v[10:13], v71 offset:32768
	ds_read_b128 v[14:17], v71 offset:33792
	ds_read_b128 v[38:41], v71 offset:34816
	ds_read_b128 v[46:49], v71 offset:35840
	ds_read_b128 v[112:115], v71 offset:36864
	ds_read_b128 v[116:119], v71 offset:37888
	ds_read_b128 v[124:127], v71 offset:38912
	ds_read_b128 v[128:131], v71 offset:39936
	global_load_lds_dwordx4 v[54:55], off
	s_mov_b32 m0, s69
	v_lshl_add_u64 v[54:55], s[10:11], 0, v[66:67]
	global_load_lds_dwordx4 v[54:55], off
	s_waitcnt vmcnt(8)
	s_waitcnt lgkmcnt(0)
	s_barrier
	s_setprio 1
	v_mfma_f32_16x16x32_bf16 v[50:53], v[6:9], v[10:13], v[50:53]
	v_mfma_f32_16x16x32_bf16 v[10:13], v[104:107], v[10:13], v[18:21]
	v_mfma_f32_16x16x32_bf16 v[58:61], v[108:111], v[14:17], v[10:13]
	v_mfma_f32_16x16x32_bf16 v[10:13], v[6:9], v[38:41], v[22:25]
	v_mfma_f32_16x16x32_bf16 v[54:57], v[80:83], v[46:49], v[10:13]
	v_mfma_f32_16x16x32_bf16 v[10:13], v[104:107], v[38:41], v[26:29]
	v_mfma_f32_16x16x32_bf16 v[62:65], v[80:83], v[14:17], v[50:53]
	v_mfma_f32_16x16x32_bf16 v[50:53], v[108:111], v[46:49], v[10:13]
	v_mfma_f32_16x16x32_bf16 v[10:13], v[6:9], v[112:115], v[30:33]
	v_mfma_f32_16x16x32_bf16 v[46:49], v[80:83], v[116:119], v[10:13]
	v_mfma_f32_16x16x32_bf16 v[10:13], v[104:107], v[112:115], v[34:37]
	v_mfma_f32_16x16x32_bf16 v[38:41], v[108:111], v[116:119], v[10:13]
	v_mfma_f32_16x16x32_bf16 v[10:13], v[6:9], v[124:127], v[84:87]
	v_mfma_f32_16x16x32_bf16 v[30:33], v[80:83], v[128:131], v[10:13]
	v_mfma_f32_16x16x32_bf16 v[10:13], v[104:107], v[124:127], v[42:45]
	v_mfma_f32_16x16x32_bf16 v[22:25], v[108:111], v[128:131], v[10:13]
	s_setprio 0
	s_barrier
	s_mov_b32 m0, vcc_lo
	v_lshl_add_u64 v[26:27], v[132:133], 0, s[64:65]
	s_add_u32 s10, s26, 0x10080
	ds_read_b128 v[10:13], v71 offset:49152
	ds_read_b128 v[14:17], v71 offset:50176
	ds_read_b128 v[18:21], v71 offset:51200
	ds_read_b128 v[84:87], v71 offset:52224
	ds_read_b128 v[112:115], v71 offset:53248
	ds_read_b128 v[116:119], v71 offset:54272
	ds_read_b128 v[124:127], v71 offset:55296
	ds_read_b128 v[128:131], v71 offset:56320
	global_load_lds_dwordx4 v[26:27], off
	v_lshl_add_u64 v[26:27], v[134:135], 0, s[64:65]
	s_mov_b32 m0, s95
	s_addc_u32 s11, s27, 0
	global_load_lds_dwordx4 v[26:27], off
	s_mov_b32 m0, s85
	v_lshl_add_u64 v[26:27], s[10:11], 0, v[68:69]
	global_load_lds_dwordx4 v[26:27], off
	s_mov_b32 m0, s88
	v_lshl_add_u64 v[26:27], s[10:11], 0, v[66:67]
	global_load_lds_dwordx4 v[26:27], off
	s_mov_b32 m0, s83
	v_lshl_add_u64 v[26:27], v[136:137], 0, s[64:65]
	global_load_lds_dwordx4 v[26:27], off
	s_mov_b32 m0, s84
	v_lshl_add_u64 v[26:27], v[138:139], 0, s[64:65]
	global_load_lds_dwordx4 v[26:27], off
	s_waitcnt vmcnt(8)
	s_waitcnt lgkmcnt(0)
	s_barrier
	s_setprio 1
	v_mfma_f32_16x16x32_bf16 v[26:29], v[6:9], v[10:13], v[88:91]
	v_mfma_f32_16x16x32_bf16 v[10:13], v[104:107], v[10:13], v[92:95]
	v_mfma_f32_16x16x32_bf16 v[34:37], v[108:111], v[14:17], v[10:13]
	v_mfma_f32_16x16x32_bf16 v[10:13], v[6:9], v[18:21], v[120:123]
	v_mfma_f32_16x16x32_bf16 v[42:45], v[80:83], v[14:17], v[26:29]
	v_mfma_f32_16x16x32_bf16 v[26:29], v[80:83], v[84:87], v[10:13]
	v_mfma_f32_16x16x32_bf16 v[10:13], v[104:107], v[18:21], v[96:99]
	v_mfma_f32_16x16x32_bf16 v[18:21], v[108:111], v[84:87], v[10:13]
	v_mfma_f32_16x16x32_bf16 v[10:13], v[6:9], v[112:115], v[100:103]
	v_mfma_f32_16x16x32_bf16 v[2:5], v[6:9], v[124:127], v[2:5]
	v_mfma_f32_16x16x32_bf16 v[14:17], v[80:83], v[116:119], v[10:13]
	v_mfma_f32_16x16x32_bf16 v[10:13], v[104:107], v[112:115], v[72:75]
	v_mfma_f32_16x16x32_bf16 v[6:9], v[80:83], v[128:131], v[2:5]
	v_mfma_f32_16x16x32_bf16 v[2:5], v[104:107], v[124:127], v[76:79]
	v_mfma_f32_16x16x32_bf16 v[10:13], v[108:111], v[116:119], v[10:13]
	v_mfma_f32_16x16x32_bf16 v[2:5], v[108:111], v[128:131], v[2:5]
	s_setprio 0
	s_barrier
	s_andn2_b64 vcc, exec, s[18:19]
	s_cbranch_vccnz .LBB0_312
	s_barrier

; #define PG8_STAGE(bufoff, gbase, voff) do { _Pragma("unroll") for (int _i = 0; _i < 2; ++_i) \
;         __builtin_amdgcn_global_load_lds((const unsigned*)((const char*)(gbase) + (voff)[_i]), (LAS unsigned*)(lds + (bufoff) + ldsw + _i * 8192), 16, 0, 0); } while (0)
; #define PG8_LDA(dst, b, h) do { _Pragma("unroll") for (int m = 0; m < 4; ++m) _Pragma("unroll") for (int k = 0; k < 2; ++k) dst[m][k] = *(const LAS bf16x8*)(lds + PG8_SA(b, h) + aoff + m * 2048 + k * 1024); } while (0)
; #define PG8_LDB(dst, b, h) do { _Pragma("unroll") for (int n = 0; n < 2; ++n) _Pragma("unroll") for (int k = 0; k < 2; ++k) dst[n][k] = *(const LAS bf16x8*)(lds + PG8_SB(b, h) + boff + n * 2048 + k * 1024); } while (0)
; #define PG8_MMA(ai, bj, At, Bt) do { __builtin_amdgcn_s_setprio(1); _Pragma("unroll") for (int m = 0; m < 4; ++m) _Pragma("unroll") for (int n = 0; n < 2; ++n) _Pragma("unroll") for (int k = 0; k < 2; ++k) \
;         acc[ai][bj][m][n] = __builtin_amdgcn_mfma_f32_16x16x32_bf16(Bt[n][k], At[m][k], acc[ai][bj][m][n], 0, 0, 0); __builtin_amdgcn_s_setprio(0); } while (0)
; #define PG8_WAIT_V(n) asm volatile("s_waitcnt vmcnt(" #n ")" ::: "memory")
; #define PG8_WAIT_L(n) asm volatile("s_waitcnt lgkmcnt(" #n ")" ::: "memory")
; #define PG8_BAR __builtin_amdgcn_s_barrier()
; #define PG8_SCHED __builtin_amdgcn_sched_barrier(0)
; template <class Epi, class Sched>
; __device__ __forceinline__ void gemm_phase(LAS unsigned char* lds, const Gemm g, const Sched S, const Epi E, const int tid) {
;     ...
;             const bool last = (t == nt - 2);
;             const char* a1 = cA + (size_t)(t + 1) * kstep;
;             const char* a2 = last ? nA : cA + (size_t)(t + 2) * kstep; const char* b2 = last ? nB : cB + (size_t)(t + 2) * kstep;
;             const char* a3 = a2 + kstep; const char* b3 = b2 + kstep;
;             PG8_LDB(B0, 0, 0); PG8_LDB(B1, 0, 1); PG8_SCHED; PG8_LDA(At, 0, 0); PG8_STAGE(PG8_SA(1, 1), a1 + hstepA, voffA);
;             PG8_WAIT_V(8); PG8_WAIT_L(0); PG8_BAR; PG8_MMA(0, 0, At, B0); PG8_MMA(0, 1, At, B1); PG8_BAR; PG8_SCHED;
;             PG8_LDA(At, 0, 1); PG8_STAGE(PG8_SB(0, 0), b2, voffB); PG8_STAGE(PG8_SB(0, 1), b2 + hstepB, voffB); PG8_STAGE(PG8_SA(0, 0), a2, voffA);
;             PG8_WAIT_V(8); PG8_WAIT_L(0); PG8_BAR; PG8_MMA(1, 0, At, B0); PG8_MMA(1, 1, At, B1); PG8_BAR; PG8_SCHED;
.LBB0_332:
	s_add_u32 s10, s44, 0xfffc0080
	s_addc_u32 s11, s45, -1
	s_add_i32 vcc_lo, 0, 0x10000
	s_cmp_eq_u32 s97, 12
	s_cselect_b32 s83, s7, s11
	s_cselect_b32 s82, s92, s10
	v_add_u32_e32 v154, vcc_lo, v157
	s_cselect_b32 s47, s93, s96
	s_cselect_b32 s46, s94, s95
	s_add_i32 vcc_hi, 0, 0x14000
	s_waitcnt lgkmcnt(0)
	ds_read_b128 v[130:133], v154
	ds_read_b128 v[134:137], v154 offset:1024
	ds_read_b128 v[150:153], v154 offset:2048
	ds_read_b128 v[160:163], v154 offset:3072
	v_add_u32_e32 v154, vcc_hi, v157
	ds_read_b128 v[164:167], v154
	ds_read_b128 v[180:183], v154 offset:1024
	ds_read_b128 v[184:187], v154 offset:2048
	ds_read_b128 v[188:191], v154 offset:3072
	v_lshl_add_u64 v[154:155], s[44:45], 0, v[148:149]
	s_add_i32 m0, s48, 0xc000
	ds_read_b128 v[192:195], v158
	ds_read_b128 v[196:199], v158 offset:1024
	ds_read_b128 v[200:203], v158 offset:2048
	ds_read_b128 v[204:207], v158 offset:3072
	ds_read_b128 v[208:211], v158 offset:4096
	ds_read_b128 v[212:215], v158 offset:5120
	ds_read_b128 v[216:219], v158 offset:6144
	ds_read_b128 v[220:223], v158 offset:7168
	global_load_lds_dwordx4 v[154:155], off
	s_add_i32 m0, s48, 0xe000
	v_lshl_add_u64 v[154:155], s[44:45], 0, v[146:147]
	global_load_lds_dwordx4 v[154:155], off
	s_waitcnt vmcnt(8)
	s_waitcnt lgkmcnt(0)
	s_barrier
	s_setprio 1
	v_mfma_f32_16x16x32_bf16 v[122:125], v[130:133], v[192:195], v[122:125]
	v_mfma_f32_16x16x32_bf16 v[114:117], v[150:153], v[192:195], v[114:117]
	v_mfma_f32_16x16x32_bf16 v[106:109], v[130:133], v[200:203], v[106:109]
	v_mfma_f32_16x16x32_bf16 v[98:101], v[150:153], v[200:203], v[98:101]
	v_mfma_f32_16x16x32_bf16 v[90:93], v[130:133], v[208:211], v[90:93]
	v_mfma_f32_16x16x32_bf16 v[82:85], v[150:153], v[208:211], v[82:85]
	v_mfma_f32_16x16x32_bf16 v[74:77], v[130:133], v[216:219], v[74:77]
	v_mfma_f32_16x16x32_bf16 v[66:69], v[150:153], v[216:219], v[66:69]
	v_mfma_f32_16x16x32_bf16 v[122:125], v[134:137], v[196:199], v[122:125]
	v_mfma_f32_16x16x32_bf16 v[114:117], v[160:163], v[196:199], v[114:117]
	v_mfma_f32_16x16x32_bf16 v[106:109], v[134:137], v[204:207], v[106:109]
	v_mfma_f32_16x16x32_bf16 v[98:101], v[160:163], v[204:207], v[98:101]
	v_mfma_f32_16x16x32_bf16 v[90:93], v[134:137], v[212:215], v[90:93]
	v_mfma_f32_16x16x32_bf16 v[82:85], v[160:163], v[212:215], v[82:85]
	v_mfma_f32_16x16x32_bf16 v[74:77], v[134:137], v[220:223], v[74:77]
	v_mfma_f32_16x16x32_bf16 v[66:69], v[160:163], v[220:223], v[66:69]
	v_mfma_f32_16x16x32_bf16 v[126:129], v[164:167], v[192:195], v[126:129]
	v_mfma_f32_16x16x32_bf16 v[118:121], v[184:187], v[192:195], v[118:121]
	v_mfma_f32_16x16x32_bf16 v[110:113], v[164:167], v[200:203], v[110:113]
	v_mfma_f32_16x16x32_bf16 v[102:105], v[184:187], v[200:203], v[102:105]
	v_mfma_f32_16x16x32_bf16 v[94:97], v[164:167], v[208:211], v[94:97]
	v_mfma_f32_16x16x32_bf16 v[86:89], v[184:187], v[208:211], v[86:89]
	v_mfma_f32_16x16x32_bf16 v[78:81], v[164:167], v[216:219], v[78:81]
	v_mfma_f32_16x16x32_bf16 v[70:73], v[184:187], v[216:219], v[70:73]
	v_mfma_f32_16x16x32_bf16 v[126:129], v[180:183], v[196:199], v[126:129]
	v_mfma_f32_16x16x32_bf16 v[118:121], v[188:191], v[196:199], v[118:121]
	v_mfma_f32_16x16x32_bf16 v[110:113], v[180:183], v[204:207], v[110:113]
	v_mfma_f32_16x16x32_bf16 v[102:105], v[188:191], v[204:207], v[102:105]
	v_mfma_f32_16x16x32_bf16 v[94:97], v[180:183], v[212:215], v[94:97]
	v_mfma_f32_16x16x32_bf16 v[86:89], v[188:191], v[212:215], v[86:89]
	v_mfma_f32_16x16x32_bf16 v[78:81], v[180:183], v[220:223], v[78:81]
	v_mfma_f32_16x16x32_bf16 v[70:73], v[188:191], v[220:223], v[70:73]
	s_setprio 0
	s_barrier
	s_add_i32 s10, vcc_lo, s37
	v_lshl_add_u64 v[154:155], s[46:47], 0, v[140:141]
	s_mov_b32 m0, s10
	ds_read_b128 v[192:195], v158 offset:16384
	ds_read_b128 v[196:199], v158 offset:17408
	ds_read_b128 v[200:203], v158 offset:18432
	ds_read_b128 v[204:207], v158 offset:19456
	ds_read_b128 v[208:211], v158 offset:20480
	ds_read_b128 v[212:215], v158 offset:21504
	ds_read_b128 v[216:219], v158 offset:22528
	ds_read_b128 v[220:223], v158 offset:23552
	global_load_lds_dwordx4 v[154:155], off
	s_add_i32 m0, s10, 0x2000
	s_add_u32 s10, s46, 0x40000
	v_lshl_add_u64 v[224:225], s[46:47], 0, v[144:145]
	s_addc_u32 s11, s47, 0
	s_add_i32 vcc_lo, vcc_hi, s37
	global_load_lds_dwordx4 v[224:225], off
	v_lshl_add_u64 v[226:227], s[10:11], 0, v[140:141]
	s_mov_b32 m0, vcc_lo
	v_lshl_add_u64 v[228:229], s[82:83], 0, v[142:143]
	global_load_lds_dwordx4 v[226:227], off
	s_add_i32 m0, vcc_lo, 0x2000
	v_lshl_add_u64 v[226:227], s[10:11], 0, v[144:145]
	global_load_lds_dwordx4 v[226:227], off
	s_mov_b32 m0, s48
	v_lshl_add_u64 v[226:227], s[82:83], 0, v[138:139]
	global_load_lds_dwordx4 v[226:227], off
	s_mov_b32 m0, s49
	s_nop 0
	global_load_lds_dwordx4 v[228:229], off
	s_waitcnt vmcnt(8)
	s_waitcnt lgkmcnt(0)
	s_barrier
; #define PG8_STAGE(bufoff, gbase, voff) do { _Pragma("unroll") for (int _i = 0; _i < 2; ++_i) \
;         __builtin_amdgcn_global_load_lds((const unsigned*)((const char*)(gbase) + (voff)[_i]), (LAS unsigned*)(lds + (bufoff) + ldsw + _i * 8192), 16, 0, 0); } while (0)
; #define PG8_LDA(dst, b, h) do { _Pragma("unroll") for (int m = 0; m < 4; ++m) _Pragma("unroll") for (int k = 0; k < 2; ++k) dst[m][k] = *(const LAS bf16x8*)(lds + PG8_SA(b, h) + aoff + m * 2048 + k * 1024); } while (0)
; #define PG8_LDB(dst, b, h) do { _Pragma("unroll") for (int n = 0; n < 2; ++n) _Pragma("unroll") for (int k = 0; k < 2; ++k) dst[n][k] = *(const LAS bf16x8*)(lds + PG8_SB(b, h) + boff + n * 2048 + k * 1024); } while (0)
; #define PG8_MMA(ai, bj, At, Bt) do { __builtin_amdgcn_s_setprio(1); _Pragma("unroll") for (int m = 0; m < 4; ++m) _Pragma("unroll") for (int n = 0; n < 2; ++n) _Pragma("unroll") for (int k = 0; k < 2; ++k) \
;         acc[ai][bj][m][n] = __builtin_amdgcn_mfma_f32_16x16x32_bf16(Bt[n][k], At[m][k], acc[ai][bj][m][n], 0, 0, 0); __builtin_amdgcn_s_setprio(0); } while (0)
; #define PG8_WAIT_V(n) asm volatile("s_waitcnt vmcnt(" #n ")" ::: "memory")
; #define PG8_WAIT_L(n) asm volatile("s_waitcnt lgkmcnt(" #n ")" ::: "memory")
; #define PG8_BAR __builtin_amdgcn_s_barrier()
; #define PG8_SCHED __builtin_amdgcn_sched_barrier(0)
; template <class Epi, class Sched>
; __device__ __forceinline__ void gemm_phase(LAS unsigned char* lds, const Gemm g, const Sched S, const Epi E, const int tid) {
;     ...
;             PG8_WAIT_V(8); PG8_WAIT_L(0); PG8_BAR; PG8_MMA(1, 0, At, B0); PG8_MMA(1, 1, At, B1); PG8_BAR; PG8_SCHED;
;             PG8_LDB(B0, 1, 0); PG8_LDB(B1, 1, 1); PG8_SCHED; PG8_LDA(At, 1, 0); PG8_STAGE(PG8_SA(0, 1), a2 + hstepA, voffA);
;             PG8_WAIT_V(8); PG8_WAIT_L(0); PG8_BAR; PG8_MMA(0, 0, At, B0); PG8_MMA(0, 1, At, B1); PG8_BAR; PG8_SCHED;
	s_setprio 1
	v_mfma_f32_16x16x32_bf16 v[58:61], v[130:133], v[192:195], v[58:61]
	v_mfma_f32_16x16x32_bf16 v[50:53], v[150:153], v[192:195], v[50:53]
	v_mfma_f32_16x16x32_bf16 v[42:45], v[130:133], v[200:203], v[42:45]
	v_mfma_f32_16x16x32_bf16 v[34:37], v[150:153], v[200:203], v[34:37]
	v_mfma_f32_16x16x32_bf16 v[26:29], v[130:133], v[208:211], v[26:29]
	v_mfma_f32_16x16x32_bf16 v[18:21], v[150:153], v[208:211], v[18:21]
	v_mfma_f32_16x16x32_bf16 v[10:13], v[130:133], v[216:219], v[10:13]
	v_mfma_f32_16x16x32_bf16 v[6:9], v[150:153], v[216:219], v[6:9]
	v_mfma_f32_16x16x32_bf16 v[58:61], v[134:137], v[196:199], v[58:61]
	v_mfma_f32_16x16x32_bf16 v[50:53], v[160:163], v[196:199], v[50:53]
	v_mfma_f32_16x16x32_bf16 v[42:45], v[134:137], v[204:207], v[42:45]
	v_mfma_f32_16x16x32_bf16 v[34:37], v[160:163], v[204:207], v[34:37]
	v_mfma_f32_16x16x32_bf16 v[26:29], v[134:137], v[212:215], v[26:29]
	v_mfma_f32_16x16x32_bf16 v[18:21], v[160:163], v[212:215], v[18:21]
	v_mfma_f32_16x16x32_bf16 v[10:13], v[134:137], v[220:223], v[10:13]
	v_mfma_f32_16x16x32_bf16 v[6:9], v[160:163], v[220:223], v[6:9]
	v_mfma_f32_16x16x32_bf16 v[62:65], v[164:167], v[192:195], v[62:65]
	v_mfma_f32_16x16x32_bf16 v[54:57], v[184:187], v[192:195], v[54:57]
	v_mfma_f32_16x16x32_bf16 v[46:49], v[164:167], v[200:203], v[46:49]
	v_mfma_f32_16x16x32_bf16 v[38:41], v[184:187], v[200:203], v[38:41]
	v_mfma_f32_16x16x32_bf16 v[30:33], v[164:167], v[208:211], v[30:33]
	v_mfma_f32_16x16x32_bf16 v[22:25], v[184:187], v[208:211], v[22:25]
	v_mfma_f32_16x16x32_bf16 v[14:17], v[164:167], v[216:219], v[14:17]
	v_mfma_f32_16x16x32_bf16 v[2:5], v[184:187], v[216:219], v[2:5]
	v_mfma_f32_16x16x32_bf16 v[62:65], v[180:183], v[196:199], v[62:65]
	v_mfma_f32_16x16x32_bf16 v[54:57], v[188:191], v[196:199], v[54:57]
	v_mfma_f32_16x16x32_bf16 v[46:49], v[180:183], v[204:207], v[46:49]
	v_mfma_f32_16x16x32_bf16 v[38:41], v[188:191], v[204:207], v[38:41]
	v_mfma_f32_16x16x32_bf16 v[30:33], v[180:183], v[212:215], v[30:33]
	v_mfma_f32_16x16x32_bf16 v[22:25], v[188:191], v[212:215], v[22:25]
	v_mfma_f32_16x16x32_bf16 v[14:17], v[180:183], v[220:223], v[14:17]
	v_mfma_f32_16x16x32_bf16 v[2:5], v[188:191], v[220:223], v[2:5]
	s_setprio 0
	s_barrier
	s_add_i32 vcc_lo, 0, 0x18000
	v_add_u32_e32 v159, vcc_lo, v157
	s_add_i32 vcc_hi, 0, 0x1c000
	ds_read_b128 v[130:133], v159
	ds_read_b128 v[134:137], v159 offset:1024
	ds_read_b128 v[150:153], v159 offset:2048
	ds_read_b128 v[160:163], v159 offset:3072
	v_add_u32_e32 v159, vcc_hi, v157
	ds_read_b128 v[164:167], v159
	ds_read_b128 v[180:183], v159 offset:1024
	ds_read_b128 v[184:187], v159 offset:2048
	ds_read_b128 v[188:191], v159 offset:3072
	s_add_u32 s10, s82, 0x40000
	s_addc_u32 s11, s83, 0
	s_mov_b32 m0, s62
	v_lshl_add_u64 v[230:231], s[10:11], 0, v[138:139]
	ds_read_b128 v[192:195], v158 offset:32768
	ds_read_b128 v[196:199], v158 offset:33792
	ds_read_b128 v[200:203], v158 offset:34816
	ds_read_b128 v[204:207], v158 offset:35840
	ds_read_b128 v[208:211], v158 offset:36864
	ds_read_b128 v[212:215], v158 offset:37888
	ds_read_b128 v[216:219], v158 offset:38912
	ds_read_b128 v[220:223], v158 offset:39936
	global_load_lds_dwordx4 v[230:231], off
	s_mov_b32 m0, s68
	v_lshl_add_u64 v[230:231], s[10:11], 0, v[142:143]
	global_load_lds_dwordx4 v[230:231], off
	s_waitcnt vmcnt(8)
	s_waitcnt lgkmcnt(0)
	s_barrier
	s_setprio 1
	v_mfma_f32_16x16x32_bf16 v[122:125], v[130:133], v[192:195], v[122:125]
	v_mfma_f32_16x16x32_bf16 v[114:117], v[150:153], v[192:195], v[114:117]
	v_mfma_f32_16x16x32_bf16 v[106:109], v[130:133], v[200:203], v[106:109]
	v_mfma_f32_16x16x32_bf16 v[98:101], v[150:153], v[200:203], v[98:101]
	v_mfma_f32_16x16x32_bf16 v[90:93], v[130:133], v[208:211], v[90:93]
	v_mfma_f32_16x16x32_bf16 v[82:85], v[150:153], v[208:211], v[82:85]
	v_mfma_f32_16x16x32_bf16 v[74:77], v[130:133], v[216:219], v[74:77]
	v_mfma_f32_16x16x32_bf16 v[66:69], v[150:153], v[216:219], v[66:69]
	v_mfma_f32_16x16x32_bf16 v[122:125], v[134:137], v[196:199], v[122:125]
	v_mfma_f32_16x16x32_bf16 v[114:117], v[160:163], v[196:199], v[114:117]
	v_mfma_f32_16x16x32_bf16 v[106:109], v[134:137], v[204:207], v[106:109]
	v_mfma_f32_16x16x32_bf16 v[98:101], v[160:163], v[204:207], v[98:101]
	v_mfma_f32_16x16x32_bf16 v[90:93], v[134:137], v[212:215], v[90:93]
	v_mfma_f32_16x16x32_bf16 v[82:85], v[160:163], v[212:215], v[82:85]
	v_mfma_f32_16x16x32_bf16 v[74:77], v[134:137], v[220:223], v[74:77]
	v_mfma_f32_16x16x32_bf16 v[66:69], v[160:163], v[220:223], v[66:69]
	v_mfma_f32_16x16x32_bf16 v[126:129], v[164:167], v[192:195], v[126:129]
	v_mfma_f32_16x16x32_bf16 v[118:121], v[184:187], v[192:195], v[118:121]
	v_mfma_f32_16x16x32_bf16 v[110:113], v[164:167], v[200:203], v[110:113]
	v_mfma_f32_16x16x32_bf16 v[102:105], v[184:187], v[200:203], v[102:105]
	v_mfma_f32_16x16x32_bf16 v[94:97], v[164:167], v[208:211], v[94:97]
	v_mfma_f32_16x16x32_bf16 v[86:89], v[184:187], v[208:211], v[86:89]
	v_mfma_f32_16x16x32_bf16 v[78:81], v[164:167], v[216:219], v[78:81]
	v_mfma_f32_16x16x32_bf16 v[70:73], v[184:187], v[216:219], v[70:73]
	v_mfma_f32_16x16x32_bf16 v[126:129], v[180:183], v[196:199], v[126:129]
	v_mfma_f32_16x16x32_bf16 v[118:121], v[188:191], v[196:199], v[118:121]
	v_mfma_f32_16x16x32_bf16 v[110:113], v[180:183], v[204:207], v[110:113]
	v_mfma_f32_16x16x32_bf16 v[102:105], v[188:191], v[204:207], v[102:105]
	v_mfma_f32_16x16x32_bf16 v[94:97], v[180:183], v[212:215], v[94:97]
	v_mfma_f32_16x16x32_bf16 v[86:89], v[188:191], v[212:215], v[86:89]
	v_mfma_f32_16x16x32_bf16 v[78:81], v[180:183], v[220:223], v[78:81]
	v_mfma_f32_16x16x32_bf16 v[70:73], v[188:191], v[220:223], v[70:73]
	s_setprio 0
	s_barrier
; #define PG8_STAGE(bufoff, gbase, voff) do { _Pragma("unroll") for (int _i = 0; _i < 2; ++_i) \
;         __builtin_amdgcn_global_load_lds((const unsigned*)((const char*)(gbase) + (voff)[_i]), (LAS unsigned*)(lds + (bufoff) + ldsw + _i * 8192), 16, 0, 0); } while (0)
; #define PG8_LDA(dst, b, h) do { _Pragma("unroll") for (int m = 0; m < 4; ++m) _Pragma("unroll") for (int k = 0; k < 2; ++k) dst[m][k] = *(const LAS bf16x8*)(lds + PG8_SA(b, h) + aoff + m * 2048 + k * 1024); } while (0)
; #define PG8_MMA(ai, bj, At, Bt) do { __builtin_amdgcn_s_setprio(1); _Pragma("unroll") for (int m = 0; m < 4; ++m) _Pragma("unroll") for (int n = 0; n < 2; ++n) _Pragma("unroll") for (int k = 0; k < 2; ++k) \
;         acc[ai][bj][m][n] = __builtin_amdgcn_mfma_f32_16x16x32_bf16(Bt[n][k], At[m][k], acc[ai][bj][m][n], 0, 0, 0); __builtin_amdgcn_s_setprio(0); } while (0)
; #define PG8_WAIT_V(n) asm volatile("s_waitcnt vmcnt(" #n ")" ::: "memory")
; #define PG8_WAIT_L(n) asm volatile("s_waitcnt lgkmcnt(" #n ")" ::: "memory")
; #define PG8_BAR __builtin_amdgcn_s_barrier()
; #define PG8_SCHED __builtin_amdgcn_sched_barrier(0)
; template <class Epi, class Sched>
; __device__ __forceinline__ void gemm_phase(LAS unsigned char* lds, const Gemm g, const Sched S, const Epi E, const int tid) {
;     ...
;             PG8_LDA(At, 1, 1); PG8_STAGE(PG8_SB(1, 0), b3, voffB); PG8_STAGE(PG8_SB(1, 1), b3 + hstepB, voffB); PG8_STAGE(PG8_SA(1, 0), a3, voffA);
;             PG8_WAIT_V(8); PG8_WAIT_L(0); PG8_BAR; PG8_MMA(1, 0, At, B0); PG8_MMA(1, 1, At, B1); PG8_BAR; PG8_SCHED;
;         }
;         if (wr == 0) PG8_BAR;
	s_add_i32 s10, vcc_lo, s37
	v_lshl_add_u64 v[154:155], v[154:155], 0, s[64:65]
	s_mov_b32 m0, s10
	ds_read_b128 v[192:195], v158 offset:49152
	ds_read_b128 v[196:199], v158 offset:50176
	ds_read_b128 v[200:203], v158 offset:51200
	ds_read_b128 v[204:207], v158 offset:52224
	ds_read_b128 v[208:211], v158 offset:53248
	ds_read_b128 v[212:215], v158 offset:54272
	ds_read_b128 v[216:219], v158 offset:55296
	ds_read_b128 v[220:223], v158 offset:56320
	global_load_lds_dwordx4 v[154:155], off
	s_add_i32 m0, s10, 0x2000
	s_add_u32 s10, s46, 0x40080
	v_lshl_add_u64 v[154:155], v[224:225], 0, s[64:65]
	s_addc_u32 s11, s47, 0
	s_add_i32 s46, vcc_hi, s37
	global_load_lds_dwordx4 v[154:155], off
	s_mov_b32 m0, s46
	v_lshl_add_u64 v[154:155], s[10:11], 0, v[140:141]
	global_load_lds_dwordx4 v[154:155], off
	s_add_i32 m0, s46, 0x2000
	v_lshl_add_u64 v[154:155], s[10:11], 0, v[144:145]
	global_load_lds_dwordx4 v[154:155], off
	s_mov_b32 m0, s88
	v_lshl_add_u64 v[154:155], v[226:227], 0, s[64:65]
	global_load_lds_dwordx4 v[154:155], off
	s_mov_b32 m0, s89
	v_lshl_add_u64 v[154:155], v[228:229], 0, s[64:65]
	global_load_lds_dwordx4 v[154:155], off
	s_waitcnt vmcnt(8)
	s_waitcnt lgkmcnt(0)
	s_barrier
	s_setprio 1
	v_mfma_f32_16x16x32_bf16 v[58:61], v[130:133], v[192:195], v[58:61]
	v_mfma_f32_16x16x32_bf16 v[50:53], v[150:153], v[192:195], v[50:53]
	v_mfma_f32_16x16x32_bf16 v[42:45], v[130:133], v[200:203], v[42:45]
	v_mfma_f32_16x16x32_bf16 v[34:37], v[150:153], v[200:203], v[34:37]
	v_mfma_f32_16x16x32_bf16 v[26:29], v[130:133], v[208:211], v[26:29]
	v_mfma_f32_16x16x32_bf16 v[18:21], v[150:153], v[208:211], v[18:21]
	v_mfma_f32_16x16x32_bf16 v[10:13], v[130:133], v[216:219], v[10:13]
	v_mfma_f32_16x16x32_bf16 v[6:9], v[150:153], v[216:219], v[6:9]
	v_mfma_f32_16x16x32_bf16 v[58:61], v[134:137], v[196:199], v[58:61]
	v_mfma_f32_16x16x32_bf16 v[50:53], v[160:163], v[196:199], v[50:53]
	v_mfma_f32_16x16x32_bf16 v[42:45], v[134:137], v[204:207], v[42:45]
	v_mfma_f32_16x16x32_bf16 v[34:37], v[160:163], v[204:207], v[34:37]
	v_mfma_f32_16x16x32_bf16 v[26:29], v[134:137], v[212:215], v[26:29]
	v_mfma_f32_16x16x32_bf16 v[18:21], v[160:163], v[212:215], v[18:21]
	v_mfma_f32_16x16x32_bf16 v[10:13], v[134:137], v[220:223], v[10:13]
	v_mfma_f32_16x16x32_bf16 v[6:9], v[160:163], v[220:223], v[6:9]
	v_mfma_f32_16x16x32_bf16 v[62:65], v[164:167], v[192:195], v[62:65]
	v_mfma_f32_16x16x32_bf16 v[54:57], v[184:187], v[192:195], v[54:57]
	v_mfma_f32_16x16x32_bf16 v[46:49], v[164:167], v[200:203], v[46:49]
	v_mfma_f32_16x16x32_bf16 v[38:41], v[184:187], v[200:203], v[38:41]
	v_mfma_f32_16x16x32_bf16 v[30:33], v[164:167], v[208:211], v[30:33]
	v_mfma_f32_16x16x32_bf16 v[22:25], v[184:187], v[208:211], v[22:25]
	v_mfma_f32_16x16x32_bf16 v[14:17], v[164:167], v[216:219], v[14:17]
	v_mfma_f32_16x16x32_bf16 v[2:5], v[184:187], v[216:219], v[2:5]
	v_mfma_f32_16x16x32_bf16 v[62:65], v[180:183], v[196:199], v[62:65]
	v_mfma_f32_16x16x32_bf16 v[54:57], v[188:191], v[196:199], v[54:57]
	v_mfma_f32_16x16x32_bf16 v[46:49], v[180:183], v[204:207], v[46:49]
	v_mfma_f32_16x16x32_bf16 v[38:41], v[188:191], v[204:207], v[38:41]
	v_mfma_f32_16x16x32_bf16 v[30:33], v[180:183], v[212:215], v[30:33]
	v_mfma_f32_16x16x32_bf16 v[22:25], v[188:191], v[212:215], v[22:25]
	v_mfma_f32_16x16x32_bf16 v[14:17], v[180:183], v[220:223], v[14:17]
	v_mfma_f32_16x16x32_bf16 v[2:5], v[188:191], v[220:223], v[2:5]
	s_setprio 0
	s_barrier
	s_add_i32 s97, s97, 2
	s_add_u32 s95, s95, 0x100
	s_addc_u32 s96, s96, 0
	s_add_u32 s44, s44, 0x100
	s_addc_u32 s45, s45, 0
	s_cmp_gt_u32 s97, 13
	s_cbranch_scc0 .LBB0_332
	s_and_b64 vcc, exec, s[14:15]
	s_cbranch_vccz .LBB0_335
	s_barrier

; #define PG8_STAGE(bufoff, gbase, voff) do { _Pragma("unroll") for (int _i = 0; _i < 2; ++_i) \
;         __builtin_amdgcn_global_load_lds((const unsigned*)((const char*)(gbase) + (voff)[_i]), (LAS unsigned*)(lds + (bufoff) + ldsw + _i * 8192), 16, 0, 0); } while (0)
; #define PG8_LDA(dst, b, h) do { _Pragma("unroll") for (int m = 0; m < 4; ++m) _Pragma("unroll") for (int k = 0; k < 2; ++k) dst[m][k] = *(const LAS bf16x8*)(lds + PG8_SA(b, h) + aoff + m * 2048 + k * 1024); } while (0)
; #define PG8_LDB(dst, b, h) do { _Pragma("unroll") for (int n = 0; n < 2; ++n) _Pragma("unroll") for (int k = 0; k < 2; ++k) dst[n][k] = *(const LAS bf16x8*)(lds + PG8_SB(b, h) + boff + n * 2048 + k * 1024); } while (0)
; #define PG8_MMA(ai, bj, At, Bt) do { __builtin_amdgcn_s_setprio(1); _Pragma("unroll") for (int m = 0; m < 4; ++m) _Pragma("unroll") for (int n = 0; n < 2; ++n) _Pragma("unroll") for (int k = 0; k < 2; ++k) \
;         acc[ai][bj][m][n] = __builtin_amdgcn_mfma_f32_16x16x32_bf16(Bt[n][k], At[m][k], acc[ai][bj][m][n], 0, 0, 0); __builtin_amdgcn_s_setprio(0); } while (0)
; #define PG8_WAIT_V(n) asm volatile("s_waitcnt vmcnt(" #n ")" ::: "memory")
; #define PG8_WAIT_L(n) asm volatile("s_waitcnt lgkmcnt(" #n ")" ::: "memory")
; #define PG8_BAR __builtin_amdgcn_s_barrier()
; #define PG8_SCHED __builtin_amdgcn_sched_barrier(0)
; template <class Epi, class Sched>
; __device__ __forceinline__ void gemm_phase(LAS unsigned char* lds, const Gemm g, const Sched S, const Epi E, const int tid) {
;     ...
;             const bool last = (t == nt - 2);
;             const char* a1 = cA + (size_t)(t + 1) * kstep;
;             const char* a2 = last ? nA : cA + (size_t)(t + 2) * kstep; const char* b2 = last ? nB : cB + (size_t)(t + 2) * kstep;
;             const char* a3 = a2 + kstep; const char* b3 = b2 + kstep;
;             PG8_LDB(B0, 0, 0); PG8_LDB(B1, 0, 1); PG8_SCHED; PG8_LDA(At, 0, 0); PG8_STAGE(PG8_SA(1, 1), a1 + hstepA, voffA);
;             PG8_WAIT_V(8); PG8_WAIT_L(0); PG8_BAR; PG8_MMA(0, 0, At, B0); PG8_MMA(0, 1, At, B1); PG8_BAR; PG8_SCHED;
;             PG8_LDA(At, 0, 1); PG8_STAGE(PG8_SB(0, 0), b2, voffB); PG8_STAGE(PG8_SB(0, 1), b2 + hstepB, voffB); PG8_STAGE(PG8_SA(0, 0), a2, voffA);
;             PG8_WAIT_V(8); PG8_WAIT_L(0); PG8_BAR; PG8_MMA(1, 0, At, B0); PG8_MMA(1, 1, At, B1); PG8_BAR; PG8_SCHED;
.LBB0_471:
	s_add_u32 s12, s10, 0xfffc0080
	s_addc_u32 s13, s11, -1
	s_add_i32 s83, 0, 0x10000
	s_cmp_eq_u32 s82, 12
	s_cselect_b32 s15, s9, s13
	s_cselect_b32 s14, s45, s12
	s_cselect_b32 s13, s43, s62
	s_cselect_b32 s12, s48, s49
	s_add_i32 vcc_lo, 0, 0x14000
	v_add_u32_e32 v154, s83, v165
	v_add_u32_e32 v162, vcc_lo, v165
	ds_read_b128 v[50:53], v154
	ds_read_b128 v[102:105], v154 offset:1024
	ds_read_b128 v[150:153], v154 offset:2048
	ds_read_b128 v[154:157], v154 offset:3072
	ds_read_b128 v[158:161], v162
	ds_read_b128 v[180:183], v162 offset:1024
	ds_read_b128 v[184:187], v162 offset:2048
	ds_read_b128 v[188:191], v162 offset:3072
	v_lshl_add_u64 v[162:163], s[10:11], 0, v[148:149]
	s_add_i32 m0, s41, 0xc000
	ds_read_b128 v[192:195], v166
	ds_read_b128 v[196:199], v166 offset:1024
	ds_read_b128 v[200:203], v166 offset:2048
	ds_read_b128 v[204:207], v166 offset:3072
	ds_read_b128 v[208:211], v166 offset:4096
	ds_read_b128 v[212:215], v166 offset:5120
	ds_read_b128 v[216:219], v166 offset:6144
	ds_read_b128 v[220:223], v166 offset:7168
	global_load_lds_dwordx4 v[162:163], off
	s_add_i32 m0, s41, 0xe000
	v_lshl_add_u64 v[162:163], s[10:11], 0, v[146:147]
	global_load_lds_dwordx4 v[162:163], off
	s_waitcnt vmcnt(8)
	s_waitcnt lgkmcnt(0)
	s_barrier
	s_setprio 1
	v_mfma_f32_16x16x32_bf16 v[130:133], v[50:53], v[192:195], v[130:133]
	v_mfma_f32_16x16x32_bf16 v[126:129], v[150:153], v[192:195], v[126:129]
	v_mfma_f32_16x16x32_bf16 v[114:117], v[50:53], v[200:203], v[114:117]
	v_mfma_f32_16x16x32_bf16 v[110:113], v[150:153], v[200:203], v[110:113]
	v_mfma_f32_16x16x32_bf16 v[94:97], v[50:53], v[208:211], v[94:97]
	v_mfma_f32_16x16x32_bf16 v[90:93], v[150:153], v[208:211], v[90:93]
	v_mfma_f32_16x16x32_bf16 v[78:81], v[50:53], v[216:219], v[78:81]
	v_mfma_f32_16x16x32_bf16 v[74:77], v[150:153], v[216:219], v[74:77]
	v_mfma_f32_16x16x32_bf16 v[130:133], v[102:105], v[196:199], v[130:133]
	v_mfma_f32_16x16x32_bf16 v[126:129], v[154:157], v[196:199], v[126:129]
	v_mfma_f32_16x16x32_bf16 v[114:117], v[102:105], v[204:207], v[114:117]
	v_mfma_f32_16x16x32_bf16 v[110:113], v[154:157], v[204:207], v[110:113]
	v_mfma_f32_16x16x32_bf16 v[94:97], v[102:105], v[212:215], v[94:97]
	v_mfma_f32_16x16x32_bf16 v[90:93], v[154:157], v[212:215], v[90:93]
	v_mfma_f32_16x16x32_bf16 v[78:81], v[102:105], v[220:223], v[78:81]
	v_mfma_f32_16x16x32_bf16 v[74:77], v[154:157], v[220:223], v[74:77]
	v_mfma_f32_16x16x32_bf16 v[134:137], v[158:161], v[192:195], v[134:137]
	v_mfma_f32_16x16x32_bf16 v[122:125], v[184:187], v[192:195], v[122:125]
	v_mfma_f32_16x16x32_bf16 v[118:121], v[158:161], v[200:203], v[118:121]
	v_mfma_f32_16x16x32_bf16 v[106:109], v[184:187], v[200:203], v[106:109]
	v_mfma_f32_16x16x32_bf16 v[98:101], v[158:161], v[208:211], v[98:101]
	v_mfma_f32_16x16x32_bf16 v[86:89], v[184:187], v[208:211], v[86:89]
	v_mfma_f32_16x16x32_bf16 v[82:85], v[158:161], v[216:219], v[82:85]
	v_mfma_f32_16x16x32_bf16 v[70:73], v[184:187], v[216:219], v[70:73]
	v_mfma_f32_16x16x32_bf16 v[134:137], v[180:183], v[196:199], v[134:137]
	v_mfma_f32_16x16x32_bf16 v[122:125], v[188:191], v[196:199], v[122:125]
	v_mfma_f32_16x16x32_bf16 v[118:121], v[180:183], v[204:207], v[118:121]
	v_mfma_f32_16x16x32_bf16 v[106:109], v[188:191], v[204:207], v[106:109]
	v_mfma_f32_16x16x32_bf16 v[98:101], v[180:183], v[212:215], v[98:101]
	v_mfma_f32_16x16x32_bf16 v[86:89], v[188:191], v[212:215], v[86:89]
	v_mfma_f32_16x16x32_bf16 v[82:85], v[180:183], v[220:223], v[82:85]
	v_mfma_f32_16x16x32_bf16 v[70:73], v[188:191], v[220:223], v[70:73]
	s_setprio 0
	s_barrier
	s_add_i32 s83, s83, s37
	v_lshl_add_u64 v[162:163], s[12:13], 0, v[140:141]
	s_mov_b32 m0, s83
	ds_read_b128 v[192:195], v166 offset:16384
	ds_read_b128 v[196:199], v166 offset:17408
	ds_read_b128 v[200:203], v166 offset:18432
	ds_read_b128 v[204:207], v166 offset:19456
	ds_read_b128 v[208:211], v166 offset:20480
	ds_read_b128 v[212:215], v166 offset:21504
	ds_read_b128 v[216:219], v166 offset:22528
	ds_read_b128 v[220:223], v166 offset:23552
	global_load_lds_dwordx4 v[162:163], off
	s_add_i32 m0, s83, 0x2000
	s_add_u32 s84, s12, 0x40000
	v_lshl_add_u64 v[224:225], s[12:13], 0, v[144:145]
	s_addc_u32 s85, s13, 0
	s_add_i32 s83, vcc_lo, s37
	global_load_lds_dwordx4 v[224:225], off
	v_lshl_add_u64 v[226:227], s[84:85], 0, v[140:141]
	s_mov_b32 m0, s83
	v_lshl_add_u64 v[228:229], s[14:15], 0, v[142:143]
	global_load_lds_dwordx4 v[226:227], off
	s_add_i32 m0, s83, 0x2000
	v_lshl_add_u64 v[226:227], s[84:85], 0, v[144:145]
	global_load_lds_dwordx4 v[226:227], off
	s_mov_b32 m0, s41
	v_lshl_add_u64 v[226:227], s[14:15], 0, v[138:139]
	global_load_lds_dwordx4 v[226:227], off
	s_mov_b32 m0, s90
	s_nop 0
	global_load_lds_dwordx4 v[228:229], off
	s_waitcnt vmcnt(8)
	s_waitcnt lgkmcnt(0)
	s_barrier
; #define PG8_STAGE(bufoff, gbase, voff) do { _Pragma("unroll") for (int _i = 0; _i < 2; ++_i) \
;         __builtin_amdgcn_global_load_lds((const unsigned*)((const char*)(gbase) + (voff)[_i]), (LAS unsigned*)(lds + (bufoff) + ldsw + _i * 8192), 16, 0, 0); } while (0)
; #define PG8_LDA(dst, b, h) do { _Pragma("unroll") for (int m = 0; m < 4; ++m) _Pragma("unroll") for (int k = 0; k < 2; ++k) dst[m][k] = *(const LAS bf16x8*)(lds + PG8_SA(b, h) + aoff + m * 2048 + k * 1024); } while (0)
; #define PG8_LDB(dst, b, h) do { _Pragma("unroll") for (int n = 0; n < 2; ++n) _Pragma("unroll") for (int k = 0; k < 2; ++k) dst[n][k] = *(const LAS bf16x8*)(lds + PG8_SB(b, h) + boff + n * 2048 + k * 1024); } while (0)
; #define PG8_MMA(ai, bj, At, Bt) do { __builtin_amdgcn_s_setprio(1); _Pragma("unroll") for (int m = 0; m < 4; ++m) _Pragma("unroll") for (int n = 0; n < 2; ++n) _Pragma("unroll") for (int k = 0; k < 2; ++k) \
;         acc[ai][bj][m][n] = __builtin_amdgcn_mfma_f32_16x16x32_bf16(Bt[n][k], At[m][k], acc[ai][bj][m][n], 0, 0, 0); __builtin_amdgcn_s_setprio(0); } while (0)
; #define PG8_WAIT_V(n) asm volatile("s_waitcnt vmcnt(" #n ")" ::: "memory")
; #define PG8_WAIT_L(n) asm volatile("s_waitcnt lgkmcnt(" #n ")" ::: "memory")
; #define PG8_BAR __builtin_amdgcn_s_barrier()
; #define PG8_SCHED __builtin_amdgcn_sched_barrier(0)
; template <class Epi, class Sched>
; __device__ __forceinline__ void gemm_phase(LAS unsigned char* lds, const Gemm g, const Sched S, const Epi E, const int tid) {
;     ...
;             PG8_WAIT_V(8); PG8_WAIT_L(0); PG8_BAR; PG8_MMA(1, 0, At, B0); PG8_MMA(1, 1, At, B1); PG8_BAR; PG8_SCHED;
;             PG8_LDB(B0, 1, 0); PG8_LDB(B1, 1, 1); PG8_SCHED; PG8_LDA(At, 1, 0); PG8_STAGE(PG8_SA(0, 1), a2 + hstepA, voffA);
;             PG8_WAIT_V(8); PG8_WAIT_L(0); PG8_BAR; PG8_MMA(0, 0, At, B0); PG8_MMA(0, 1, At, B1); PG8_BAR; PG8_SCHED;
	s_setprio 1
	v_mfma_f32_16x16x32_bf16 v[62:65], v[50:53], v[192:195], v[62:65]
	v_mfma_f32_16x16x32_bf16 v[58:61], v[150:153], v[192:195], v[58:61]
	v_mfma_f32_16x16x32_bf16 v[42:45], v[50:53], v[200:203], v[42:45]
	v_mfma_f32_16x16x32_bf16 v[38:41], v[150:153], v[200:203], v[38:41]
	v_mfma_f32_16x16x32_bf16 v[26:29], v[50:53], v[208:211], v[26:29]
	v_mfma_f32_16x16x32_bf16 v[22:25], v[150:153], v[208:211], v[22:25]
	v_mfma_f32_16x16x32_bf16 v[10:13], v[50:53], v[216:219], v[10:13]
	v_mfma_f32_16x16x32_bf16 v[6:9], v[150:153], v[216:219], v[6:9]
	v_mfma_f32_16x16x32_bf16 v[62:65], v[102:105], v[196:199], v[62:65]
	v_mfma_f32_16x16x32_bf16 v[58:61], v[154:157], v[196:199], v[58:61]
	v_mfma_f32_16x16x32_bf16 v[42:45], v[102:105], v[204:207], v[42:45]
	v_mfma_f32_16x16x32_bf16 v[38:41], v[154:157], v[204:207], v[38:41]
	v_mfma_f32_16x16x32_bf16 v[26:29], v[102:105], v[212:215], v[26:29]
	v_mfma_f32_16x16x32_bf16 v[22:25], v[154:157], v[212:215], v[22:25]
	v_mfma_f32_16x16x32_bf16 v[10:13], v[102:105], v[220:223], v[10:13]
	v_mfma_f32_16x16x32_bf16 v[6:9], v[154:157], v[220:223], v[6:9]
	v_mfma_f32_16x16x32_bf16 v[54:57], v[184:187], v[192:195], v[54:57]
	v_mfma_f32_16x16x32_bf16 v[46:49], v[158:161], v[200:203], v[46:49]
	v_mfma_f32_16x16x32_bf16 v[34:37], v[184:187], v[200:203], v[34:37]
	v_mfma_f32_16x16x32_bf16 v[30:33], v[158:161], v[208:211], v[30:33]
	v_mfma_f32_16x16x32_bf16 v[18:21], v[184:187], v[208:211], v[18:21]
	v_mfma_f32_16x16x32_bf16 v[14:17], v[158:161], v[216:219], v[14:17]
	v_mfma_f32_16x16x32_bf16 v[2:5], v[184:187], v[216:219], v[2:5]
	v_mfma_f32_16x16x32_bf16 v[50:53], v[158:161], v[192:195], v[66:69]
	v_mfma_f32_16x16x32_bf16 v[54:57], v[188:191], v[196:199], v[54:57]
	v_mfma_f32_16x16x32_bf16 v[46:49], v[180:183], v[204:207], v[46:49]
	v_mfma_f32_16x16x32_bf16 v[34:37], v[188:191], v[204:207], v[34:37]
	v_mfma_f32_16x16x32_bf16 v[30:33], v[180:183], v[212:215], v[30:33]
	v_mfma_f32_16x16x32_bf16 v[18:21], v[188:191], v[212:215], v[18:21]
	v_mfma_f32_16x16x32_bf16 v[14:17], v[180:183], v[220:223], v[14:17]
	v_mfma_f32_16x16x32_bf16 v[2:5], v[188:191], v[220:223], v[2:5]
	v_mfma_f32_16x16x32_bf16 v[50:53], v[180:183], v[196:199], v[50:53]
	s_setprio 0
	s_barrier
	s_add_i32 s83, 0, 0x18000
	s_add_i32 s84, 0, 0x1c000
	v_add_u32_e32 v154, s83, v165
	v_add_u32_e32 v167, s84, v165
	ds_read_b128 v[66:69], v154
	ds_read_b128 v[102:105], v154 offset:1024
	ds_read_b128 v[150:153], v154 offset:2048
	ds_read_b128 v[154:157], v154 offset:3072
	ds_read_b128 v[158:161], v167
	ds_read_b128 v[180:183], v167 offset:1024
	ds_read_b128 v[184:187], v167 offset:2048
	ds_read_b128 v[188:191], v167 offset:3072
	s_add_u32 s14, s14, 0x40000
	s_addc_u32 s15, s15, 0
	s_mov_b32 m0, s91
	v_lshl_add_u64 v[230:231], s[14:15], 0, v[138:139]
	ds_read_b128 v[192:195], v166 offset:32768
	ds_read_b128 v[196:199], v166 offset:33792
	ds_read_b128 v[200:203], v166 offset:34816
	ds_read_b128 v[204:207], v166 offset:35840
	ds_read_b128 v[208:211], v166 offset:36864
	ds_read_b128 v[212:215], v166 offset:37888
	ds_read_b128 v[216:219], v166 offset:38912
	ds_read_b128 v[220:223], v166 offset:39936
	global_load_lds_dwordx4 v[230:231], off
	s_mov_b32 m0, s68
	v_lshl_add_u64 v[230:231], s[14:15], 0, v[142:143]
	global_load_lds_dwordx4 v[230:231], off
	s_waitcnt vmcnt(8)
	s_waitcnt lgkmcnt(0)
	s_barrier
	s_setprio 1
	v_mfma_f32_16x16x32_bf16 v[130:133], v[66:69], v[192:195], v[130:133]
	v_mfma_f32_16x16x32_bf16 v[126:129], v[150:153], v[192:195], v[126:129]
	v_mfma_f32_16x16x32_bf16 v[114:117], v[66:69], v[200:203], v[114:117]
	v_mfma_f32_16x16x32_bf16 v[110:113], v[150:153], v[200:203], v[110:113]
	v_mfma_f32_16x16x32_bf16 v[94:97], v[66:69], v[208:211], v[94:97]
	v_mfma_f32_16x16x32_bf16 v[90:93], v[150:153], v[208:211], v[90:93]
	v_mfma_f32_16x16x32_bf16 v[78:81], v[66:69], v[216:219], v[78:81]
	v_mfma_f32_16x16x32_bf16 v[74:77], v[150:153], v[216:219], v[74:77]
	v_mfma_f32_16x16x32_bf16 v[130:133], v[102:105], v[196:199], v[130:133]
	v_mfma_f32_16x16x32_bf16 v[126:129], v[154:157], v[196:199], v[126:129]
	v_mfma_f32_16x16x32_bf16 v[114:117], v[102:105], v[204:207], v[114:117]
	v_mfma_f32_16x16x32_bf16 v[110:113], v[154:157], v[204:207], v[110:113]
	v_mfma_f32_16x16x32_bf16 v[94:97], v[102:105], v[212:215], v[94:97]
	v_mfma_f32_16x16x32_bf16 v[90:93], v[154:157], v[212:215], v[90:93]
	v_mfma_f32_16x16x32_bf16 v[78:81], v[102:105], v[220:223], v[78:81]
	v_mfma_f32_16x16x32_bf16 v[74:77], v[154:157], v[220:223], v[74:77]
	v_mfma_f32_16x16x32_bf16 v[134:137], v[158:161], v[192:195], v[134:137]
	v_mfma_f32_16x16x32_bf16 v[122:125], v[184:187], v[192:195], v[122:125]
	v_mfma_f32_16x16x32_bf16 v[118:121], v[158:161], v[200:203], v[118:121]
	v_mfma_f32_16x16x32_bf16 v[106:109], v[184:187], v[200:203], v[106:109]
	v_mfma_f32_16x16x32_bf16 v[98:101], v[158:161], v[208:211], v[98:101]
	v_mfma_f32_16x16x32_bf16 v[86:89], v[184:187], v[208:211], v[86:89]
	v_mfma_f32_16x16x32_bf16 v[82:85], v[158:161], v[216:219], v[82:85]
	v_mfma_f32_16x16x32_bf16 v[70:73], v[184:187], v[216:219], v[70:73]
	v_mfma_f32_16x16x32_bf16 v[134:137], v[180:183], v[196:199], v[134:137]
	v_mfma_f32_16x16x32_bf16 v[122:125], v[188:191], v[196:199], v[122:125]
	v_mfma_f32_16x16x32_bf16 v[118:121], v[180:183], v[204:207], v[118:121]
	v_mfma_f32_16x16x32_bf16 v[106:109], v[188:191], v[204:207], v[106:109]
	v_mfma_f32_16x16x32_bf16 v[98:101], v[180:183], v[212:215], v[98:101]
	v_mfma_f32_16x16x32_bf16 v[86:89], v[188:191], v[212:215], v[86:89]
	v_mfma_f32_16x16x32_bf16 v[82:85], v[180:183], v[220:223], v[82:85]
	v_mfma_f32_16x16x32_bf16 v[70:73], v[188:191], v[220:223], v[70:73]
	s_setprio 0
	s_barrier
; #define PG8_STAGE(bufoff, gbase, voff) do { _Pragma("unroll") for (int _i = 0; _i < 2; ++_i) \
;         __builtin_amdgcn_global_load_lds((const unsigned*)((const char*)(gbase) + (voff)[_i]), (LAS unsigned*)(lds + (bufoff) + ldsw + _i * 8192), 16, 0, 0); } while (0)
; #define PG8_LDA(dst, b, h) do { _Pragma("unroll") for (int m = 0; m < 4; ++m) _Pragma("unroll") for (int k = 0; k < 2; ++k) dst[m][k] = *(const LAS bf16x8*)(lds + PG8_SA(b, h) + aoff + m * 2048 + k * 1024); } while (0)
; #define PG8_MMA(ai, bj, At, Bt) do { __builtin_amdgcn_s_setprio(1); _Pragma("unroll") for (int m = 0; m < 4; ++m) _Pragma("unroll") for (int n = 0; n < 2; ++n) _Pragma("unroll") for (int k = 0; k < 2; ++k) \
;         acc[ai][bj][m][n] = __builtin_amdgcn_mfma_f32_16x16x32_bf16(Bt[n][k], At[m][k], acc[ai][bj][m][n], 0, 0, 0); __builtin_amdgcn_s_setprio(0); } while (0)
; #define PG8_WAIT_V(n) asm volatile("s_waitcnt vmcnt(" #n ")" ::: "memory")
; #define PG8_WAIT_L(n) asm volatile("s_waitcnt lgkmcnt(" #n ")" ::: "memory")
; #define PG8_BAR __builtin_amdgcn_s_barrier()
; #define PG8_SCHED __builtin_amdgcn_sched_barrier(0)
; template <class Epi, class Sched>
; __device__ __forceinline__ void gemm_phase(LAS unsigned char* lds, const Gemm g, const Sched S, const Epi E, const int tid) {
;     ...
;             PG8_LDA(At, 1, 1); PG8_STAGE(PG8_SB(1, 0), b3, voffB); PG8_STAGE(PG8_SB(1, 1), b3 + hstepB, voffB); PG8_STAGE(PG8_SA(1, 0), a3, voffA);
;             PG8_WAIT_V(8); PG8_WAIT_L(0); PG8_BAR; PG8_MMA(1, 0, At, B0); PG8_MMA(1, 1, At, B1); PG8_BAR; PG8_SCHED;
;         }
;         if (wr == 0) PG8_BAR;
	s_add_i32 s14, s83, s37
	v_lshl_add_u64 v[162:163], v[162:163], 0, s[64:65]
	s_mov_b32 m0, s14
	ds_read_b128 v[192:195], v166 offset:49152
	ds_read_b128 v[196:199], v166 offset:50176
	ds_read_b128 v[200:203], v166 offset:51200
	ds_read_b128 v[204:207], v166 offset:52224
	ds_read_b128 v[208:211], v166 offset:53248
	ds_read_b128 v[212:215], v166 offset:54272
	ds_read_b128 v[216:219], v166 offset:55296
	ds_read_b128 v[220:223], v166 offset:56320
	global_load_lds_dwordx4 v[162:163], off
	s_add_i32 m0, s14, 0x2000
	s_add_u32 s12, s12, 0x40080
	v_lshl_add_u64 v[162:163], v[224:225], 0, s[64:65]
	s_addc_u32 s13, s13, 0
	s_add_i32 s14, s84, s37
	global_load_lds_dwordx4 v[162:163], off
	s_mov_b32 m0, s14
	v_lshl_add_u64 v[162:163], s[12:13], 0, v[140:141]
	global_load_lds_dwordx4 v[162:163], off
	s_add_i32 m0, s14, 0x2000
	v_lshl_add_u64 v[162:163], s[12:13], 0, v[144:145]
	global_load_lds_dwordx4 v[162:163], off
	s_mov_b32 m0, s29
	v_lshl_add_u64 v[162:163], v[226:227], 0, s[64:65]
	global_load_lds_dwordx4 v[162:163], off
	s_mov_b32 m0, s92
	v_lshl_add_u64 v[162:163], v[228:229], 0, s[64:65]
	global_load_lds_dwordx4 v[162:163], off
	s_waitcnt vmcnt(8)
	s_waitcnt lgkmcnt(0)
	s_barrier
	s_setprio 1
	v_mfma_f32_16x16x32_bf16 v[62:65], v[66:69], v[192:195], v[62:65]
	v_mfma_f32_16x16x32_bf16 v[58:61], v[150:153], v[192:195], v[58:61]
	v_mfma_f32_16x16x32_bf16 v[42:45], v[66:69], v[200:203], v[42:45]
	v_mfma_f32_16x16x32_bf16 v[38:41], v[150:153], v[200:203], v[38:41]
	v_mfma_f32_16x16x32_bf16 v[26:29], v[66:69], v[208:211], v[26:29]
	v_mfma_f32_16x16x32_bf16 v[22:25], v[150:153], v[208:211], v[22:25]
	v_mfma_f32_16x16x32_bf16 v[10:13], v[66:69], v[216:219], v[10:13]
	v_mfma_f32_16x16x32_bf16 v[6:9], v[150:153], v[216:219], v[6:9]
	v_mfma_f32_16x16x32_bf16 v[62:65], v[102:105], v[196:199], v[62:65]
	v_mfma_f32_16x16x32_bf16 v[58:61], v[154:157], v[196:199], v[58:61]
	v_mfma_f32_16x16x32_bf16 v[42:45], v[102:105], v[204:207], v[42:45]
	v_mfma_f32_16x16x32_bf16 v[38:41], v[154:157], v[204:207], v[38:41]
	v_mfma_f32_16x16x32_bf16 v[26:29], v[102:105], v[212:215], v[26:29]
	v_mfma_f32_16x16x32_bf16 v[22:25], v[154:157], v[212:215], v[22:25]
	v_mfma_f32_16x16x32_bf16 v[10:13], v[102:105], v[220:223], v[10:13]
	v_mfma_f32_16x16x32_bf16 v[6:9], v[154:157], v[220:223], v[6:9]
	v_mfma_f32_16x16x32_bf16 v[50:53], v[158:161], v[192:195], v[50:53]
	v_mfma_f32_16x16x32_bf16 v[66:69], v[180:183], v[196:199], v[50:53]
	v_mfma_f32_16x16x32_bf16 v[50:53], v[184:187], v[192:195], v[54:57]
	v_mfma_f32_16x16x32_bf16 v[46:49], v[158:161], v[200:203], v[46:49]
	v_mfma_f32_16x16x32_bf16 v[34:37], v[184:187], v[200:203], v[34:37]
	v_mfma_f32_16x16x32_bf16 v[30:33], v[158:161], v[208:211], v[30:33]
	v_mfma_f32_16x16x32_bf16 v[18:21], v[184:187], v[208:211], v[18:21]
	v_mfma_f32_16x16x32_bf16 v[14:17], v[158:161], v[216:219], v[14:17]
	v_mfma_f32_16x16x32_bf16 v[2:5], v[184:187], v[216:219], v[2:5]
	v_mfma_f32_16x16x32_bf16 v[54:57], v[188:191], v[196:199], v[50:53]
	v_mfma_f32_16x16x32_bf16 v[46:49], v[180:183], v[204:207], v[46:49]
	v_mfma_f32_16x16x32_bf16 v[34:37], v[188:191], v[204:207], v[34:37]
	v_mfma_f32_16x16x32_bf16 v[30:33], v[180:183], v[212:215], v[30:33]
	v_mfma_f32_16x16x32_bf16 v[18:21], v[188:191], v[212:215], v[18:21]
	v_mfma_f32_16x16x32_bf16 v[14:17], v[180:183], v[220:223], v[14:17]
	v_mfma_f32_16x16x32_bf16 v[2:5], v[188:191], v[220:223], v[2:5]
	s_setprio 0
	s_barrier
	s_add_i32 s82, s82, 2
	s_add_u32 s49, s49, 0x100
	s_addc_u32 s62, s62, 0
	s_add_u32 s10, s10, 0x100
	s_addc_u32 s11, s11, 0
	s_cmp_gt_u32 s82, 13
	s_cbranch_scc0 .LBB0_471
	s_and_b64 vcc, exec, s[18:19]
	s_cbranch_vccz .LBB0_474
	s_barrier

; #define PG8_STAGE(bufoff, gbase, voff) do { _Pragma("unroll") for (int _i = 0; _i < 2; ++_i) \
;         __builtin_amdgcn_global_load_lds((const unsigned*)((const char*)(gbase) + (voff)[_i]), (LAS unsigned*)(lds + (bufoff) + ldsw + _i * 8192), 16, 0, 0); } while (0)
; #define PG8_LDA(dst, b, h) do { _Pragma("unroll") for (int m = 0; m < 4; ++m) _Pragma("unroll") for (int k = 0; k < 2; ++k) dst[m][k] = *(const LAS bf16x8*)(lds + PG8_SA(b, h) + aoff + m * 2048 + k * 1024); } while (0)
; #define PG8_LDB(dst, b, h) do { _Pragma("unroll") for (int n = 0; n < 2; ++n) _Pragma("unroll") for (int k = 0; k < 2; ++k) dst[n][k] = *(const LAS bf16x8*)(lds + PG8_SB(b, h) + boff + n * 2048 + k * 1024); } while (0)
; #define PG8_MMA(ai, bj, At, Bt) do { __builtin_amdgcn_s_setprio(1); _Pragma("unroll") for (int m = 0; m < 4; ++m) _Pragma("unroll") for (int n = 0; n < 2; ++n) _Pragma("unroll") for (int k = 0; k < 2; ++k) \
;         acc[ai][bj][m][n] = __builtin_amdgcn_mfma_f32_16x16x32_bf16(Bt[n][k], At[m][k], acc[ai][bj][m][n], 0, 0, 0); __builtin_amdgcn_s_setprio(0); } while (0)
; #define PG8_WAIT_V(n) asm volatile("s_waitcnt vmcnt(" #n ")" ::: "memory")
; #define PG8_WAIT_L(n) asm volatile("s_waitcnt lgkmcnt(" #n ")" ::: "memory")
; #define PG8_BAR __builtin_amdgcn_s_barrier()
; #define PG8_SCHED __builtin_amdgcn_sched_barrier(0)
; template <class Epi, class Sched>
; __device__ __forceinline__ void gemm_phase(LAS unsigned char* lds, const Gemm g, const Sched S, const Epi E, const int tid) {
;     ...
;             const bool last = (t == nt - 2);
;             const char* a1 = cA + (size_t)(t + 1) * kstep;
;             const char* a2 = last ? nA : cA + (size_t)(t + 2) * kstep; const char* b2 = last ? nB : cB + (size_t)(t + 2) * kstep;
;             const char* a3 = a2 + kstep; const char* b3 = b2 + kstep;
;             PG8_LDB(B0, 0, 0); PG8_LDB(B1, 0, 1); PG8_SCHED; PG8_LDA(At, 0, 0); PG8_STAGE(PG8_SA(1, 1), a1 + hstepA, voffA);
;             PG8_WAIT_V(8); PG8_WAIT_L(0); PG8_BAR; PG8_MMA(0, 0, At, B0); PG8_MMA(0, 1, At, B1); PG8_BAR; PG8_SCHED;
;             PG8_LDA(At, 0, 1); PG8_STAGE(PG8_SB(0, 0), b2, voffB); PG8_STAGE(PG8_SB(0, 1), b2 + hstepB, voffB); PG8_STAGE(PG8_SA(0, 0), a2, voffA);
;             PG8_WAIT_V(8); PG8_WAIT_L(0); PG8_BAR; PG8_MMA(1, 0, At, B0); PG8_MMA(1, 1, At, B1); PG8_BAR; PG8_SCHED;
.LBB0_778:
	s_add_i32 s94, s20, 2
	s_add_u32 s95, s18, 0x80
	s_addc_u32 s21, s19, 0
	s_add_i32 vcc_lo, 0, 0x10000
	s_cmp_eq_u32 s69, s20
	s_cselect_b32 s21, s9, s21
	s_cselect_b32 s20, s8, s95
	s_cselect_b32 s97, s17, s93
	s_cselect_b32 s96, s16, s92
	s_add_i32 s95, 0, 0x14000
	v_add_u32_e32 v142, vcc_lo, v198
	v_add_u32_e32 v167, s95, v198
	ds_read_b128 v[126:129], v142
	ds_read_b128 v[134:137], v142 offset:1024
	ds_read_b128 v[138:141], v142 offset:2048
	ds_read_b128 v[142:145], v142 offset:3072
	ds_read_b128 v[146:149], v167
	ds_read_b128 v[150:153], v167 offset:1024
	ds_read_b128 v[154:157], v167 offset:2048
	ds_read_b128 v[186:189], v167 offset:3072
	v_lshl_add_u64 v[224:225], s[18:19], 0, v[184:185]
	s_add_i32 m0, s37, 0xc000
	ds_read_b128 v[190:193], v199
	ds_read_b128 v[194:197], v199 offset:1024
	ds_read_b128 v[200:203], v199 offset:2048
	ds_read_b128 v[204:207], v199 offset:3072
	ds_read_b128 v[208:211], v199 offset:4096
	ds_read_b128 v[212:215], v199 offset:5120
	ds_read_b128 v[216:219], v199 offset:6144
	ds_read_b128 v[220:223], v199 offset:7168
	global_load_lds_dwordx4 v[224:225], off
	s_add_i32 m0, s37, 0xe000
	v_lshl_add_u64 v[224:225], s[18:19], 0, v[182:183]
	global_load_lds_dwordx4 v[224:225], off
	s_waitcnt vmcnt(8)
	s_waitcnt lgkmcnt(0)
	s_barrier
	s_setprio 1
	v_mfma_f32_16x16x32_bf16 v[130:133], v[126:129], v[190:193], v[130:133]
	v_mfma_f32_16x16x32_bf16 v[122:125], v[138:141], v[190:193], v[122:125]
	v_mfma_f32_16x16x32_bf16 v[110:113], v[126:129], v[200:203], v[110:113]
	v_mfma_f32_16x16x32_bf16 v[106:109], v[138:141], v[200:203], v[106:109]
	v_mfma_f32_16x16x32_bf16 v[94:97], v[126:129], v[208:211], v[94:97]
	v_mfma_f32_16x16x32_bf16 v[90:93], v[138:141], v[208:211], v[90:93]
	v_mfma_f32_16x16x32_bf16 v[78:81], v[126:129], v[216:219], v[78:81]
	v_mfma_f32_16x16x32_bf16 v[74:77], v[138:141], v[216:219], v[74:77]
	v_mfma_f32_16x16x32_bf16 v[130:133], v[134:137], v[194:197], v[130:133]
	v_mfma_f32_16x16x32_bf16 v[122:125], v[142:145], v[194:197], v[122:125]
	v_mfma_f32_16x16x32_bf16 v[110:113], v[134:137], v[204:207], v[110:113]
	v_mfma_f32_16x16x32_bf16 v[106:109], v[142:145], v[204:207], v[106:109]
	v_mfma_f32_16x16x32_bf16 v[94:97], v[134:137], v[212:215], v[94:97]
	v_mfma_f32_16x16x32_bf16 v[90:93], v[142:145], v[212:215], v[90:93]
	v_mfma_f32_16x16x32_bf16 v[78:81], v[134:137], v[220:223], v[78:81]
	v_mfma_f32_16x16x32_bf16 v[74:77], v[142:145], v[220:223], v[74:77]
	v_mfma_f32_16x16x32_bf16 v[118:121], v[146:149], v[190:193], v[118:121]
	v_mfma_f32_16x16x32_bf16 v[114:117], v[154:157], v[190:193], v[114:117]
	v_mfma_f32_16x16x32_bf16 v[102:105], v[146:149], v[200:203], v[102:105]
	v_mfma_f32_16x16x32_bf16 v[98:101], v[154:157], v[200:203], v[98:101]
	v_mfma_f32_16x16x32_bf16 v[86:89], v[146:149], v[208:211], v[86:89]
	v_mfma_f32_16x16x32_bf16 v[82:85], v[154:157], v[208:211], v[82:85]
	v_mfma_f32_16x16x32_bf16 v[70:73], v[146:149], v[216:219], v[70:73]
	v_mfma_f32_16x16x32_bf16 v[66:69], v[154:157], v[216:219], v[66:69]
	v_mfma_f32_16x16x32_bf16 v[118:121], v[150:153], v[194:197], v[118:121]
	v_mfma_f32_16x16x32_bf16 v[114:117], v[186:189], v[194:197], v[114:117]
	v_mfma_f32_16x16x32_bf16 v[102:105], v[150:153], v[204:207], v[102:105]
	v_mfma_f32_16x16x32_bf16 v[98:101], v[186:189], v[204:207], v[98:101]
	v_mfma_f32_16x16x32_bf16 v[86:89], v[150:153], v[212:215], v[86:89]
	v_mfma_f32_16x16x32_bf16 v[82:85], v[186:189], v[212:215], v[82:85]
	v_mfma_f32_16x16x32_bf16 v[70:73], v[150:153], v[220:223], v[70:73]
	v_mfma_f32_16x16x32_bf16 v[66:69], v[186:189], v[220:223], v[66:69]
	s_setprio 0
	s_barrier
	s_add_i32 vcc_lo, vcc_lo, s29
	v_lshl_add_u64 v[224:225], s[96:97], 0, v[160:161]
	s_mov_b32 m0, vcc_lo
	ds_read_b128 v[190:193], v199 offset:16384
	ds_read_b128 v[194:197], v199 offset:17408
	ds_read_b128 v[200:203], v199 offset:18432
	ds_read_b128 v[204:207], v199 offset:19456
	ds_read_b128 v[208:211], v199 offset:20480
	ds_read_b128 v[212:215], v199 offset:21504
	ds_read_b128 v[216:219], v199 offset:22528
	ds_read_b128 v[220:223], v199 offset:23552
	global_load_lds_dwordx4 v[224:225], off
	s_add_i32 m0, vcc_lo, 0x2000
	v_lshl_add_u64 v[226:227], s[96:97], 0, v[164:165]
	s_add_u32 s96, s96, s62
	s_addc_u32 s97, s97, 0
	s_add_i32 s95, s95, s29
	global_load_lds_dwordx4 v[226:227], off
	v_lshl_add_u64 v[228:229], s[96:97], 0, v[160:161]
	s_mov_b32 m0, s95
	v_lshl_add_u64 v[230:231], s[96:97], 0, v[164:165]
	global_load_lds_dwordx4 v[228:229], off
	s_add_i32 m0, s95, 0x2000
	v_lshl_add_u64 v[232:233], s[20:21], 0, v[158:159]
	global_load_lds_dwordx4 v[230:231], off
	s_mov_b32 m0, s37
	v_lshl_add_u64 v[234:235], s[20:21], 0, v[162:163]
	global_load_lds_dwordx4 v[232:233], off
	s_mov_b32 m0, s40
	s_nop 0
	global_load_lds_dwordx4 v[234:235], off
	s_waitcnt vmcnt(8)
	s_waitcnt lgkmcnt(0)
	s_barrier
; #define PG8_STAGE(bufoff, gbase, voff) do { _Pragma("unroll") for (int _i = 0; _i < 2; ++_i) \
;         __builtin_amdgcn_global_load_lds((const unsigned*)((const char*)(gbase) + (voff)[_i]), (LAS unsigned*)(lds + (bufoff) + ldsw + _i * 8192), 16, 0, 0); } while (0)
; #define PG8_LDA(dst, b, h) do { _Pragma("unroll") for (int m = 0; m < 4; ++m) _Pragma("unroll") for (int k = 0; k < 2; ++k) dst[m][k] = *(const LAS bf16x8*)(lds + PG8_SA(b, h) + aoff + m * 2048 + k * 1024); } while (0)
; #define PG8_LDB(dst, b, h) do { _Pragma("unroll") for (int n = 0; n < 2; ++n) _Pragma("unroll") for (int k = 0; k < 2; ++k) dst[n][k] = *(const LAS bf16x8*)(lds + PG8_SB(b, h) + boff + n * 2048 + k * 1024); } while (0)
; #define PG8_MMA(ai, bj, At, Bt) do { __builtin_amdgcn_s_setprio(1); _Pragma("unroll") for (int m = 0; m < 4; ++m) _Pragma("unroll") for (int n = 0; n < 2; ++n) _Pragma("unroll") for (int k = 0; k < 2; ++k) \
;         acc[ai][bj][m][n] = __builtin_amdgcn_mfma_f32_16x16x32_bf16(Bt[n][k], At[m][k], acc[ai][bj][m][n], 0, 0, 0); __builtin_amdgcn_s_setprio(0); } while (0)
; #define PG8_WAIT_V(n) asm volatile("s_waitcnt vmcnt(" #n ")" ::: "memory")
; #define PG8_WAIT_L(n) asm volatile("s_waitcnt lgkmcnt(" #n ")" ::: "memory")
; #define PG8_BAR __builtin_amdgcn_s_barrier()
; #define PG8_SCHED __builtin_amdgcn_sched_barrier(0)
; template <class Epi, class Sched>
; __device__ __forceinline__ void gemm_phase(LAS unsigned char* lds, const Gemm g, const Sched S, const Epi E, const int tid) {
;     ...
;             PG8_WAIT_V(8); PG8_WAIT_L(0); PG8_BAR; PG8_MMA(1, 0, At, B0); PG8_MMA(1, 1, At, B1); PG8_BAR; PG8_SCHED;
;             PG8_LDB(B0, 1, 0); PG8_LDB(B1, 1, 1); PG8_SCHED; PG8_LDA(At, 1, 0); PG8_STAGE(PG8_SA(0, 1), a2 + hstepA, voffA);
;             PG8_WAIT_V(8); PG8_WAIT_L(0); PG8_BAR; PG8_MMA(0, 0, At, B0); PG8_MMA(0, 1, At, B1); PG8_BAR; PG8_SCHED;
	s_setprio 1
	v_mfma_f32_16x16x32_bf16 v[62:65], v[126:129], v[190:193], v[62:65]
	v_mfma_f32_16x16x32_bf16 v[58:61], v[138:141], v[190:193], v[58:61]
	v_mfma_f32_16x16x32_bf16 v[46:49], v[126:129], v[200:203], v[46:49]
	v_mfma_f32_16x16x32_bf16 v[42:45], v[138:141], v[200:203], v[42:45]
	v_mfma_f32_16x16x32_bf16 v[30:33], v[126:129], v[208:211], v[30:33]
	v_mfma_f32_16x16x32_bf16 v[26:29], v[138:141], v[208:211], v[26:29]
	v_mfma_f32_16x16x32_bf16 v[14:17], v[126:129], v[216:219], v[14:17]
	v_mfma_f32_16x16x32_bf16 v[10:13], v[138:141], v[216:219], v[10:13]
	v_mfma_f32_16x16x32_bf16 v[62:65], v[134:137], v[194:197], v[62:65]
	v_mfma_f32_16x16x32_bf16 v[58:61], v[142:145], v[194:197], v[58:61]
	v_mfma_f32_16x16x32_bf16 v[46:49], v[134:137], v[204:207], v[46:49]
	v_mfma_f32_16x16x32_bf16 v[42:45], v[142:145], v[204:207], v[42:45]
	v_mfma_f32_16x16x32_bf16 v[30:33], v[134:137], v[212:215], v[30:33]
	v_mfma_f32_16x16x32_bf16 v[26:29], v[142:145], v[212:215], v[26:29]
	v_mfma_f32_16x16x32_bf16 v[14:17], v[134:137], v[220:223], v[14:17]
	v_mfma_f32_16x16x32_bf16 v[10:13], v[142:145], v[220:223], v[10:13]
	v_mfma_f32_16x16x32_bf16 v[54:57], v[146:149], v[190:193], v[54:57]
	v_mfma_f32_16x16x32_bf16 v[50:53], v[154:157], v[190:193], v[50:53]
	v_mfma_f32_16x16x32_bf16 v[38:41], v[146:149], v[200:203], v[38:41]
	v_mfma_f32_16x16x32_bf16 v[34:37], v[154:157], v[200:203], v[34:37]
	v_mfma_f32_16x16x32_bf16 v[22:25], v[146:149], v[208:211], v[22:25]
	v_mfma_f32_16x16x32_bf16 v[18:21], v[154:157], v[208:211], v[18:21]
	v_mfma_f32_16x16x32_bf16 v[6:9], v[146:149], v[216:219], v[6:9]
	v_mfma_f32_16x16x32_bf16 v[2:5], v[154:157], v[216:219], v[2:5]
	v_mfma_f32_16x16x32_bf16 v[54:57], v[150:153], v[194:197], v[54:57]
	v_mfma_f32_16x16x32_bf16 v[50:53], v[186:189], v[194:197], v[50:53]
	v_mfma_f32_16x16x32_bf16 v[38:41], v[150:153], v[204:207], v[38:41]
	v_mfma_f32_16x16x32_bf16 v[34:37], v[186:189], v[204:207], v[34:37]
	v_mfma_f32_16x16x32_bf16 v[22:25], v[150:153], v[212:215], v[22:25]
	v_mfma_f32_16x16x32_bf16 v[18:21], v[186:189], v[212:215], v[18:21]
	v_mfma_f32_16x16x32_bf16 v[6:9], v[150:153], v[220:223], v[6:9]
	v_mfma_f32_16x16x32_bf16 v[2:5], v[186:189], v[220:223], v[2:5]
	s_setprio 0
	s_barrier
	s_add_i32 s95, 0, 0x18000
	s_add_i32 s96, 0, 0x1c000
	v_add_u32_e32 v142, s95, v198
	v_add_u32_e32 v167, s96, v198
	ds_read_b128 v[126:129], v142
	ds_read_b128 v[134:137], v142 offset:1024
	ds_read_b128 v[138:141], v142 offset:2048
	ds_read_b128 v[142:145], v142 offset:3072
	ds_read_b128 v[146:149], v167
	ds_read_b128 v[150:153], v167 offset:1024
	ds_read_b128 v[154:157], v167 offset:2048
	ds_read_b128 v[186:189], v167 offset:3072
	s_add_u32 s20, s20, s62
	s_addc_u32 s21, s21, 0
	s_mov_b32 m0, s41
	v_lshl_add_u64 v[246:247], s[20:21], 0, v[158:159]
	ds_read_b128 v[190:193], v199 offset:32768
	ds_read_b128 v[194:197], v199 offset:33792
	ds_read_b128 v[200:203], v199 offset:34816
	ds_read_b128 v[204:207], v199 offset:35840
	ds_read_b128 v[208:211], v199 offset:36864
	ds_read_b128 v[212:215], v199 offset:37888
	ds_read_b128 v[216:219], v199 offset:38912
	ds_read_b128 v[220:223], v199 offset:39936
	global_load_lds_dwordx4 v[246:247], off
	s_mov_b32 m0, s42
	v_lshl_add_u64 v[246:247], s[20:21], 0, v[162:163]
	global_load_lds_dwordx4 v[246:247], off
	s_waitcnt vmcnt(8)
	s_waitcnt lgkmcnt(0)
	s_barrier
	s_setprio 1
	v_mfma_f32_16x16x32_bf16 v[130:133], v[126:129], v[190:193], v[130:133]
	v_mfma_f32_16x16x32_bf16 v[122:125], v[138:141], v[190:193], v[122:125]
	v_mfma_f32_16x16x32_bf16 v[110:113], v[126:129], v[200:203], v[110:113]
	v_mfma_f32_16x16x32_bf16 v[106:109], v[138:141], v[200:203], v[106:109]
	v_mfma_f32_16x16x32_bf16 v[94:97], v[126:129], v[208:211], v[94:97]
	v_mfma_f32_16x16x32_bf16 v[90:93], v[138:141], v[208:211], v[90:93]
	v_mfma_f32_16x16x32_bf16 v[78:81], v[126:129], v[216:219], v[78:81]
	v_mfma_f32_16x16x32_bf16 v[74:77], v[138:141], v[216:219], v[74:77]
	v_mfma_f32_16x16x32_bf16 v[130:133], v[134:137], v[194:197], v[130:133]
	v_mfma_f32_16x16x32_bf16 v[122:125], v[142:145], v[194:197], v[122:125]
	v_mfma_f32_16x16x32_bf16 v[110:113], v[134:137], v[204:207], v[110:113]
	v_mfma_f32_16x16x32_bf16 v[106:109], v[142:145], v[204:207], v[106:109]
	v_mfma_f32_16x16x32_bf16 v[94:97], v[134:137], v[212:215], v[94:97]
	v_mfma_f32_16x16x32_bf16 v[90:93], v[142:145], v[212:215], v[90:93]
	v_mfma_f32_16x16x32_bf16 v[78:81], v[134:137], v[220:223], v[78:81]
	v_mfma_f32_16x16x32_bf16 v[74:77], v[142:145], v[220:223], v[74:77]
	v_mfma_f32_16x16x32_bf16 v[118:121], v[146:149], v[190:193], v[118:121]
	v_mfma_f32_16x16x32_bf16 v[114:117], v[154:157], v[190:193], v[114:117]
	v_mfma_f32_16x16x32_bf16 v[102:105], v[146:149], v[200:203], v[102:105]
	v_mfma_f32_16x16x32_bf16 v[98:101], v[154:157], v[200:203], v[98:101]
	v_mfma_f32_16x16x32_bf16 v[86:89], v[146:149], v[208:211], v[86:89]
	v_mfma_f32_16x16x32_bf16 v[82:85], v[154:157], v[208:211], v[82:85]
	v_mfma_f32_16x16x32_bf16 v[70:73], v[146:149], v[216:219], v[70:73]
	v_mfma_f32_16x16x32_bf16 v[66:69], v[154:157], v[216:219], v[66:69]
	v_mfma_f32_16x16x32_bf16 v[118:121], v[150:153], v[194:197], v[118:121]
	v_mfma_f32_16x16x32_bf16 v[114:117], v[186:189], v[194:197], v[114:117]
	v_mfma_f32_16x16x32_bf16 v[102:105], v[150:153], v[204:207], v[102:105]
	v_mfma_f32_16x16x32_bf16 v[98:101], v[186:189], v[204:207], v[98:101]
	v_mfma_f32_16x16x32_bf16 v[86:89], v[150:153], v[212:215], v[86:89]
	v_mfma_f32_16x16x32_bf16 v[82:85], v[186:189], v[212:215], v[82:85]
	v_mfma_f32_16x16x32_bf16 v[70:73], v[150:153], v[220:223], v[70:73]
	v_mfma_f32_16x16x32_bf16 v[66:69], v[186:189], v[220:223], v[66:69]
	s_setprio 0
	s_barrier
; #define PG8_STAGE(bufoff, gbase, voff) do { _Pragma("unroll") for (int _i = 0; _i < 2; ++_i) \
;         __builtin_amdgcn_global_load_lds((const unsigned*)((const char*)(gbase) + (voff)[_i]), (LAS unsigned*)(lds + (bufoff) + ldsw + _i * 8192), 16, 0, 0); } while (0)
; #define PG8_LDA(dst, b, h) do { _Pragma("unroll") for (int m = 0; m < 4; ++m) _Pragma("unroll") for (int k = 0; k < 2; ++k) dst[m][k] = *(const LAS bf16x8*)(lds + PG8_SA(b, h) + aoff + m * 2048 + k * 1024); } while (0)
; #define PG8_MMA(ai, bj, At, Bt) do { __builtin_amdgcn_s_setprio(1); _Pragma("unroll") for (int m = 0; m < 4; ++m) _Pragma("unroll") for (int n = 0; n < 2; ++n) _Pragma("unroll") for (int k = 0; k < 2; ++k) \
;         acc[ai][bj][m][n] = __builtin_amdgcn_mfma_f32_16x16x32_bf16(Bt[n][k], At[m][k], acc[ai][bj][m][n], 0, 0, 0); __builtin_amdgcn_s_setprio(0); } while (0)
; #define PG8_WAIT_V(n) asm volatile("s_waitcnt vmcnt(" #n ")" ::: "memory")
; #define PG8_WAIT_L(n) asm volatile("s_waitcnt lgkmcnt(" #n ")" ::: "memory")
; #define PG8_BAR __builtin_amdgcn_s_barrier()
; #define PG8_SCHED __builtin_amdgcn_sched_barrier(0)
; template <class Epi, class Sched>
; __device__ __forceinline__ void gemm_phase(LAS unsigned char* lds, const Gemm g, const Sched S, const Epi E, const int tid) {
;     ...
;             PG8_LDA(At, 1, 1); PG8_STAGE(PG8_SB(1, 0), b3, voffB); PG8_STAGE(PG8_SB(1, 1), b3 + hstepB, voffB); PG8_STAGE(PG8_SA(1, 0), a3, voffA);
;             PG8_WAIT_V(8); PG8_WAIT_L(0); PG8_BAR; PG8_MMA(1, 0, At, B0); PG8_MMA(1, 1, At, B1); PG8_BAR; PG8_SCHED;
;         }
;         if (wr == 0) PG8_BAR;
	s_add_i32 s20, s95, s29
	v_lshl_add_u64 v[224:225], v[224:225], 0, s[64:65]
	s_mov_b32 m0, s20
	ds_read_b128 v[190:193], v199 offset:49152
	ds_read_b128 v[194:197], v199 offset:50176
	ds_read_b128 v[200:203], v199 offset:51200
	ds_read_b128 v[204:207], v199 offset:52224
	ds_read_b128 v[208:211], v199 offset:53248
	ds_read_b128 v[212:215], v199 offset:54272
	ds_read_b128 v[216:219], v199 offset:55296
	ds_read_b128 v[220:223], v199 offset:56320
	global_load_lds_dwordx4 v[224:225], off
	v_lshl_add_u64 v[224:225], v[226:227], 0, s[64:65]
	s_add_i32 m0, s20, 0x2000
	s_add_i32 s20, s96, s29
	global_load_lds_dwordx4 v[224:225], off
	s_mov_b32 m0, s20
	v_lshl_add_u64 v[224:225], v[228:229], 0, s[64:65]
	global_load_lds_dwordx4 v[224:225], off
	s_add_i32 m0, s20, 0x2000
	v_lshl_add_u64 v[224:225], v[230:231], 0, s[64:65]
	global_load_lds_dwordx4 v[224:225], off
	s_mov_b32 m0, s45
	v_lshl_add_u64 v[224:225], v[232:233], 0, s[64:65]
	global_load_lds_dwordx4 v[224:225], off
	s_mov_b32 m0, s46
	v_lshl_add_u64 v[224:225], v[234:235], 0, s[64:65]
	global_load_lds_dwordx4 v[224:225], off
	s_waitcnt vmcnt(8)
	s_waitcnt lgkmcnt(0)
	s_barrier
	s_setprio 1
	v_mfma_f32_16x16x32_bf16 v[62:65], v[126:129], v[190:193], v[62:65]
	v_mfma_f32_16x16x32_bf16 v[58:61], v[138:141], v[190:193], v[58:61]
	v_mfma_f32_16x16x32_bf16 v[46:49], v[126:129], v[200:203], v[46:49]
	v_mfma_f32_16x16x32_bf16 v[42:45], v[138:141], v[200:203], v[42:45]
	v_mfma_f32_16x16x32_bf16 v[30:33], v[126:129], v[208:211], v[30:33]
	v_mfma_f32_16x16x32_bf16 v[26:29], v[138:141], v[208:211], v[26:29]
	v_mfma_f32_16x16x32_bf16 v[14:17], v[126:129], v[216:219], v[14:17]
	v_mfma_f32_16x16x32_bf16 v[10:13], v[138:141], v[216:219], v[10:13]
	v_mfma_f32_16x16x32_bf16 v[62:65], v[134:137], v[194:197], v[62:65]
	v_mfma_f32_16x16x32_bf16 v[58:61], v[142:145], v[194:197], v[58:61]
	v_mfma_f32_16x16x32_bf16 v[46:49], v[134:137], v[204:207], v[46:49]
	v_mfma_f32_16x16x32_bf16 v[42:45], v[142:145], v[204:207], v[42:45]
	v_mfma_f32_16x16x32_bf16 v[30:33], v[134:137], v[212:215], v[30:33]
	v_mfma_f32_16x16x32_bf16 v[26:29], v[142:145], v[212:215], v[26:29]
	v_mfma_f32_16x16x32_bf16 v[14:17], v[134:137], v[220:223], v[14:17]
	v_mfma_f32_16x16x32_bf16 v[10:13], v[142:145], v[220:223], v[10:13]
	v_mfma_f32_16x16x32_bf16 v[54:57], v[146:149], v[190:193], v[54:57]
	v_mfma_f32_16x16x32_bf16 v[50:53], v[154:157], v[190:193], v[50:53]
	v_mfma_f32_16x16x32_bf16 v[38:41], v[146:149], v[200:203], v[38:41]
	v_mfma_f32_16x16x32_bf16 v[34:37], v[154:157], v[200:203], v[34:37]
	v_mfma_f32_16x16x32_bf16 v[22:25], v[146:149], v[208:211], v[22:25]
	v_mfma_f32_16x16x32_bf16 v[18:21], v[154:157], v[208:211], v[18:21]
	v_mfma_f32_16x16x32_bf16 v[6:9], v[146:149], v[216:219], v[6:9]
	v_mfma_f32_16x16x32_bf16 v[2:5], v[154:157], v[216:219], v[2:5]
	v_mfma_f32_16x16x32_bf16 v[54:57], v[150:153], v[194:197], v[54:57]
	v_mfma_f32_16x16x32_bf16 v[50:53], v[186:189], v[194:197], v[50:53]
	v_mfma_f32_16x16x32_bf16 v[38:41], v[150:153], v[204:207], v[38:41]
	v_mfma_f32_16x16x32_bf16 v[34:37], v[186:189], v[204:207], v[34:37]
	v_mfma_f32_16x16x32_bf16 v[22:25], v[150:153], v[212:215], v[22:25]
	v_mfma_f32_16x16x32_bf16 v[18:21], v[186:189], v[212:215], v[18:21]
	v_mfma_f32_16x16x32_bf16 v[6:9], v[150:153], v[220:223], v[6:9]
	v_mfma_f32_16x16x32_bf16 v[2:5], v[186:189], v[220:223], v[2:5]
	s_setprio 0
	s_barrier
	s_add_u32 s92, s92, 0x100
	s_addc_u32 s93, s93, 0
	s_add_u32 s18, s18, 0x100
	s_addc_u32 s19, s19, 0
	s_cmp_ge_u32 s94, s47
	s_mov_b32 s20, s94
	s_cbranch_scc0 .LBB0_778
	s_and_b64 vcc, exec, s[12:13]
	s_cbranch_vccz .LBB0_781
	s_barrier

; #define PG8_STAGE(bufoff, gbase, voff) do { _Pragma("unroll") for (int _i = 0; _i < 2; ++_i) \
;         __builtin_amdgcn_global_load_lds((const unsigned*)((const char*)(gbase) + (voff)[_i]), (LAS unsigned*)(lds + (bufoff) + ldsw + _i * 8192), 16, 0, 0); } while (0)
; #define PG8_LDA(dst, b, h) do { _Pragma("unroll") for (int m = 0; m < 4; ++m) _Pragma("unroll") for (int k = 0; k < 2; ++k) dst[m][k] = *(const LAS bf16x8*)(lds + PG8_SA(b, h) + aoff + m * 2048 + k * 1024); } while (0)
; #define PG8_LDB(dst, b, h) do { _Pragma("unroll") for (int n = 0; n < 2; ++n) _Pragma("unroll") for (int k = 0; k < 2; ++k) dst[n][k] = *(const LAS bf16x8*)(lds + PG8_SB(b, h) + boff + n * 2048 + k * 1024); } while (0)
; #define PG8_MMA(ai, bj, At, Bt) do { __builtin_amdgcn_s_setprio(1); _Pragma("unroll") for (int m = 0; m < 4; ++m) _Pragma("unroll") for (int n = 0; n < 2; ++n) _Pragma("unroll") for (int k = 0; k < 2; ++k) \
;         acc[ai][bj][m][n] = __builtin_amdgcn_mfma_f32_16x16x32_bf16(Bt[n][k], At[m][k], acc[ai][bj][m][n], 0, 0, 0); __builtin_amdgcn_s_setprio(0); } while (0)
; #define PG8_WAIT_V(n) asm volatile("s_waitcnt vmcnt(" #n ")" ::: "memory")
; #define PG8_WAIT_L(n) asm volatile("s_waitcnt lgkmcnt(" #n ")" ::: "memory")
; #define PG8_BAR __builtin_amdgcn_s_barrier()
; #define PG8_SCHED __builtin_amdgcn_sched_barrier(0)
; template <class Epi, class Sched>
; __device__ __forceinline__ void gemm_phase(LAS unsigned char* lds, const Gemm g, const Sched S, const Epi E, const int tid) {
;     ...
;             const bool last = (t == nt - 2);
;             const char* a1 = cA + (size_t)(t + 1) * kstep;
;             const char* a2 = last ? nA : cA + (size_t)(t + 2) * kstep; const char* b2 = last ? nB : cB + (size_t)(t + 2) * kstep;
;             const char* a3 = a2 + kstep; const char* b3 = b2 + kstep;
;             PG8_LDB(B0, 0, 0); PG8_LDB(B1, 0, 1); PG8_SCHED; PG8_LDA(At, 0, 0); PG8_STAGE(PG8_SA(1, 1), a1 + hstepA, voffA);
;             PG8_WAIT_V(8); PG8_WAIT_L(0); PG8_BAR; PG8_MMA(0, 0, At, B0); PG8_MMA(0, 1, At, B1); PG8_BAR; PG8_SCHED;
;             PG8_LDA(At, 0, 1); PG8_STAGE(PG8_SB(0, 0), b2, voffB); PG8_STAGE(PG8_SB(0, 1), b2 + hstepB, voffB); PG8_STAGE(PG8_SA(0, 0), a2, voffA);
;             PG8_WAIT_V(8); PG8_WAIT_L(0); PG8_BAR; PG8_MMA(1, 0, At, B0); PG8_MMA(1, 1, At, B1); PG8_BAR; PG8_SCHED;
.LBB0_819:
	s_add_u32 s24, s22, 0xfffc0080
	s_addc_u32 s25, s23, -1
	s_add_i32 s85, 0, 0x10000
	s_cmp_eq_u32 s84, 12
	s_cselect_b32 s27, s9, s25
	s_cselect_b32 s26, s17, s24
	s_cselect_b32 s25, s15, s83
	s_cselect_b32 s24, s69, s82
	s_add_i32 s90, 0, 0x14000
	v_add_u32_e32 v154, s85, v165
	v_add_u32_e32 v162, s90, v165
	ds_read_b128 v[98:101], v154
	ds_read_b128 v[134:137], v154 offset:1024
	ds_read_b128 v[150:153], v154 offset:2048
	ds_read_b128 v[154:157], v154 offset:3072
	ds_read_b128 v[158:161], v162
	ds_read_b128 v[180:183], v162 offset:1024
	ds_read_b128 v[184:187], v162 offset:2048
	ds_read_b128 v[188:191], v162 offset:3072
	v_lshl_add_u64 v[162:163], s[22:23], 0, v[148:149]
	s_add_i32 m0, s40, 0xc000
	ds_read_b128 v[192:195], v166
	ds_read_b128 v[196:199], v166 offset:1024
	ds_read_b128 v[200:203], v166 offset:2048
	ds_read_b128 v[204:207], v166 offset:3072
	ds_read_b128 v[208:211], v166 offset:4096
	ds_read_b128 v[212:215], v166 offset:5120
	ds_read_b128 v[216:219], v166 offset:6144
	ds_read_b128 v[220:223], v166 offset:7168
	global_load_lds_dwordx4 v[162:163], off
	s_add_i32 m0, s40, 0xe000
	v_lshl_add_u64 v[162:163], s[22:23], 0, v[146:147]
	global_load_lds_dwordx4 v[162:163], off
	s_waitcnt vmcnt(8)
	s_waitcnt lgkmcnt(0)
	s_barrier
	s_setprio 1
	v_mfma_f32_16x16x32_bf16 v[130:133], v[98:101], v[192:195], v[130:133]
	v_mfma_f32_16x16x32_bf16 v[118:121], v[150:153], v[192:195], v[118:121]
	v_mfma_f32_16x16x32_bf16 v[114:117], v[98:101], v[200:203], v[114:117]
	v_mfma_f32_16x16x32_bf16 v[102:105], v[150:153], v[200:203], v[102:105]
	v_mfma_f32_16x16x32_bf16 v[94:97], v[98:101], v[208:211], v[94:97]
	v_mfma_f32_16x16x32_bf16 v[82:85], v[150:153], v[208:211], v[82:85]
	v_mfma_f32_16x16x32_bf16 v[78:81], v[98:101], v[216:219], v[78:81]
	v_mfma_f32_16x16x32_bf16 v[66:69], v[150:153], v[216:219], v[66:69]
	v_mfma_f32_16x16x32_bf16 v[130:133], v[134:137], v[196:199], v[130:133]
	v_mfma_f32_16x16x32_bf16 v[118:121], v[154:157], v[196:199], v[118:121]
	v_mfma_f32_16x16x32_bf16 v[114:117], v[134:137], v[204:207], v[114:117]
	v_mfma_f32_16x16x32_bf16 v[102:105], v[154:157], v[204:207], v[102:105]
	v_mfma_f32_16x16x32_bf16 v[94:97], v[134:137], v[212:215], v[94:97]
	v_mfma_f32_16x16x32_bf16 v[82:85], v[154:157], v[212:215], v[82:85]
	v_mfma_f32_16x16x32_bf16 v[78:81], v[134:137], v[220:223], v[78:81]
	v_mfma_f32_16x16x32_bf16 v[66:69], v[154:157], v[220:223], v[66:69]
	v_mfma_f32_16x16x32_bf16 v[126:129], v[158:161], v[192:195], v[126:129]
	v_mfma_f32_16x16x32_bf16 v[122:125], v[184:187], v[192:195], v[122:125]
	v_mfma_f32_16x16x32_bf16 v[110:113], v[158:161], v[200:203], v[110:113]
	v_mfma_f32_16x16x32_bf16 v[106:109], v[184:187], v[200:203], v[106:109]
	v_mfma_f32_16x16x32_bf16 v[90:93], v[158:161], v[208:211], v[90:93]
	v_mfma_f32_16x16x32_bf16 v[86:89], v[184:187], v[208:211], v[86:89]
	v_mfma_f32_16x16x32_bf16 v[74:77], v[158:161], v[216:219], v[74:77]
	v_mfma_f32_16x16x32_bf16 v[70:73], v[184:187], v[216:219], v[70:73]
	v_mfma_f32_16x16x32_bf16 v[126:129], v[180:183], v[196:199], v[126:129]
	v_mfma_f32_16x16x32_bf16 v[122:125], v[188:191], v[196:199], v[122:125]
	v_mfma_f32_16x16x32_bf16 v[110:113], v[180:183], v[204:207], v[110:113]
	v_mfma_f32_16x16x32_bf16 v[106:109], v[188:191], v[204:207], v[106:109]
	v_mfma_f32_16x16x32_bf16 v[90:93], v[180:183], v[212:215], v[90:93]
	v_mfma_f32_16x16x32_bf16 v[86:89], v[188:191], v[212:215], v[86:89]
	v_mfma_f32_16x16x32_bf16 v[74:77], v[180:183], v[220:223], v[74:77]
	v_mfma_f32_16x16x32_bf16 v[70:73], v[188:191], v[220:223], v[70:73]
	s_setprio 0
	s_barrier
	s_add_i32 s85, s85, s28
	v_lshl_add_u64 v[162:163], s[24:25], 0, v[142:143]
	s_mov_b32 m0, s85
	ds_read_b128 v[192:195], v166 offset:16384
	ds_read_b128 v[196:199], v166 offset:17408
	ds_read_b128 v[200:203], v166 offset:18432
	ds_read_b128 v[204:207], v166 offset:19456
	ds_read_b128 v[208:211], v166 offset:20480
	ds_read_b128 v[212:215], v166 offset:21504
	ds_read_b128 v[216:219], v166 offset:22528
	ds_read_b128 v[220:223], v166 offset:23552
	global_load_lds_dwordx4 v[162:163], off
	s_add_i32 m0, s85, 0x2000
	s_add_u32 s88, s24, 0x40000
	v_lshl_add_u64 v[224:225], s[24:25], 0, v[138:139]
	s_addc_u32 s89, s25, 0
	s_add_i32 s85, s90, s28
	global_load_lds_dwordx4 v[224:225], off
	v_lshl_add_u64 v[226:227], s[88:89], 0, v[142:143]
	s_mov_b32 m0, s85
	v_lshl_add_u64 v[228:229], s[26:27], 0, v[140:141]
	global_load_lds_dwordx4 v[226:227], off
	s_add_i32 m0, s85, 0x2000
	v_lshl_add_u64 v[226:227], s[88:89], 0, v[138:139]
	global_load_lds_dwordx4 v[226:227], off
	s_mov_b32 m0, s40
	v_lshl_add_u64 v[226:227], s[26:27], 0, v[144:145]
	global_load_lds_dwordx4 v[226:227], off
	s_mov_b32 m0, s41
	s_nop 0
	global_load_lds_dwordx4 v[228:229], off
	s_waitcnt vmcnt(8)
	s_waitcnt lgkmcnt(0)
	s_barrier
; #define PG8_STAGE(bufoff, gbase, voff) do { _Pragma("unroll") for (int _i = 0; _i < 2; ++_i) \
;         __builtin_amdgcn_global_load_lds((const unsigned*)((const char*)(gbase) + (voff)[_i]), (LAS unsigned*)(lds + (bufoff) + ldsw + _i * 8192), 16, 0, 0); } while (0)
; #define PG8_LDA(dst, b, h) do { _Pragma("unroll") for (int m = 0; m < 4; ++m) _Pragma("unroll") for (int k = 0; k < 2; ++k) dst[m][k] = *(const LAS bf16x8*)(lds + PG8_SA(b, h) + aoff + m * 2048 + k * 1024); } while (0)
; #define PG8_LDB(dst, b, h) do { _Pragma("unroll") for (int n = 0; n < 2; ++n) _Pragma("unroll") for (int k = 0; k < 2; ++k) dst[n][k] = *(const LAS bf16x8*)(lds + PG8_SB(b, h) + boff + n * 2048 + k * 1024); } while (0)
; #define PG8_MMA(ai, bj, At, Bt) do { __builtin_amdgcn_s_setprio(1); _Pragma("unroll") for (int m = 0; m < 4; ++m) _Pragma("unroll") for (int n = 0; n < 2; ++n) _Pragma("unroll") for (int k = 0; k < 2; ++k) \
;         acc[ai][bj][m][n] = __builtin_amdgcn_mfma_f32_16x16x32_bf16(Bt[n][k], At[m][k], acc[ai][bj][m][n], 0, 0, 0); __builtin_amdgcn_s_setprio(0); } while (0)
; #define PG8_WAIT_V(n) asm volatile("s_waitcnt vmcnt(" #n ")" ::: "memory")
; #define PG8_WAIT_L(n) asm volatile("s_waitcnt lgkmcnt(" #n ")" ::: "memory")
; #define PG8_BAR __builtin_amdgcn_s_barrier()
; #define PG8_SCHED __builtin_amdgcn_sched_barrier(0)
; template <class Epi, class Sched>
; __device__ __forceinline__ void gemm_phase(LAS unsigned char* lds, const Gemm g, const Sched S, const Epi E, const int tid) {
;     ...
;             PG8_WAIT_V(8); PG8_WAIT_L(0); PG8_BAR; PG8_MMA(1, 0, At, B0); PG8_MMA(1, 1, At, B1); PG8_BAR; PG8_SCHED;
;             PG8_LDB(B0, 1, 0); PG8_LDB(B1, 1, 1); PG8_SCHED; PG8_LDA(At, 1, 0); PG8_STAGE(PG8_SA(0, 1), a2 + hstepA, voffA);
;             PG8_WAIT_V(8); PG8_WAIT_L(0); PG8_BAR; PG8_MMA(0, 0, At, B0); PG8_MMA(0, 1, At, B1); PG8_BAR; PG8_SCHED;
	s_setprio 1
	v_mfma_f32_16x16x32_bf16 v[62:65], v[98:101], v[192:195], v[62:65]
	v_mfma_f32_16x16x32_bf16 v[50:53], v[150:153], v[192:195], v[50:53]
	v_mfma_f32_16x16x32_bf16 v[46:49], v[98:101], v[200:203], v[46:49]
	v_mfma_f32_16x16x32_bf16 v[34:37], v[150:153], v[200:203], v[34:37]
	v_mfma_f32_16x16x32_bf16 v[30:33], v[98:101], v[208:211], v[30:33]
	v_mfma_f32_16x16x32_bf16 v[18:21], v[150:153], v[208:211], v[18:21]
	v_mfma_f32_16x16x32_bf16 v[14:17], v[98:101], v[216:219], v[14:17]
	v_mfma_f32_16x16x32_bf16 v[6:9], v[150:153], v[216:219], v[6:9]
	v_mfma_f32_16x16x32_bf16 v[62:65], v[134:137], v[196:199], v[62:65]
	v_mfma_f32_16x16x32_bf16 v[50:53], v[154:157], v[196:199], v[50:53]
	v_mfma_f32_16x16x32_bf16 v[46:49], v[134:137], v[204:207], v[46:49]
	v_mfma_f32_16x16x32_bf16 v[34:37], v[154:157], v[204:207], v[34:37]
	v_mfma_f32_16x16x32_bf16 v[30:33], v[134:137], v[212:215], v[30:33]
	v_mfma_f32_16x16x32_bf16 v[18:21], v[154:157], v[212:215], v[18:21]
	v_mfma_f32_16x16x32_bf16 v[14:17], v[134:137], v[220:223], v[14:17]
	v_mfma_f32_16x16x32_bf16 v[6:9], v[154:157], v[220:223], v[6:9]
	v_mfma_f32_16x16x32_bf16 v[58:61], v[158:161], v[192:195], v[58:61]
	v_mfma_f32_16x16x32_bf16 v[54:57], v[184:187], v[192:195], v[54:57]
	v_mfma_f32_16x16x32_bf16 v[42:45], v[158:161], v[200:203], v[42:45]
	v_mfma_f32_16x16x32_bf16 v[38:41], v[184:187], v[200:203], v[38:41]
	v_mfma_f32_16x16x32_bf16 v[26:29], v[158:161], v[208:211], v[26:29]
	v_mfma_f32_16x16x32_bf16 v[22:25], v[184:187], v[208:211], v[22:25]
	v_mfma_f32_16x16x32_bf16 v[10:13], v[158:161], v[216:219], v[10:13]
	v_mfma_f32_16x16x32_bf16 v[2:5], v[184:187], v[216:219], v[2:5]
	v_mfma_f32_16x16x32_bf16 v[58:61], v[180:183], v[196:199], v[58:61]
	v_mfma_f32_16x16x32_bf16 v[54:57], v[188:191], v[196:199], v[54:57]
	v_mfma_f32_16x16x32_bf16 v[42:45], v[180:183], v[204:207], v[42:45]
	v_mfma_f32_16x16x32_bf16 v[38:41], v[188:191], v[204:207], v[38:41]
	v_mfma_f32_16x16x32_bf16 v[26:29], v[180:183], v[212:215], v[26:29]
	v_mfma_f32_16x16x32_bf16 v[22:25], v[188:191], v[212:215], v[22:25]
	v_mfma_f32_16x16x32_bf16 v[10:13], v[180:183], v[220:223], v[10:13]
	v_mfma_f32_16x16x32_bf16 v[2:5], v[188:191], v[220:223], v[2:5]
	s_setprio 0
	s_barrier
	s_add_i32 s85, 0, 0x18000
	s_add_i32 s88, 0, 0x1c000
	v_add_u32_e32 v154, s85, v165
	v_add_u32_e32 v167, s88, v165
	ds_read_b128 v[98:101], v154
	ds_read_b128 v[134:137], v154 offset:1024
	ds_read_b128 v[150:153], v154 offset:2048
	ds_read_b128 v[154:157], v154 offset:3072
	ds_read_b128 v[158:161], v167
	ds_read_b128 v[180:183], v167 offset:1024
	ds_read_b128 v[184:187], v167 offset:2048
	ds_read_b128 v[188:191], v167 offset:3072
	s_add_u32 s26, s26, 0x40000
	s_addc_u32 s27, s27, 0
	s_mov_b32 m0, s42
	v_lshl_add_u64 v[230:231], s[26:27], 0, v[144:145]
	ds_read_b128 v[192:195], v166 offset:32768
	ds_read_b128 v[196:199], v166 offset:33792
	ds_read_b128 v[200:203], v166 offset:34816
	ds_read_b128 v[204:207], v166 offset:35840
	ds_read_b128 v[208:211], v166 offset:36864
	ds_read_b128 v[212:215], v166 offset:37888
	ds_read_b128 v[216:219], v166 offset:38912
	ds_read_b128 v[220:223], v166 offset:39936
	global_load_lds_dwordx4 v[230:231], off
	s_mov_b32 m0, s43
	v_lshl_add_u64 v[230:231], s[26:27], 0, v[140:141]
	global_load_lds_dwordx4 v[230:231], off
	s_waitcnt vmcnt(8)
	s_waitcnt lgkmcnt(0)
	s_barrier
	s_setprio 1
	v_mfma_f32_16x16x32_bf16 v[130:133], v[98:101], v[192:195], v[130:133]
	v_mfma_f32_16x16x32_bf16 v[118:121], v[150:153], v[192:195], v[118:121]
	v_mfma_f32_16x16x32_bf16 v[114:117], v[98:101], v[200:203], v[114:117]
	v_mfma_f32_16x16x32_bf16 v[102:105], v[150:153], v[200:203], v[102:105]
	v_mfma_f32_16x16x32_bf16 v[94:97], v[98:101], v[208:211], v[94:97]
	v_mfma_f32_16x16x32_bf16 v[82:85], v[150:153], v[208:211], v[82:85]
	v_mfma_f32_16x16x32_bf16 v[78:81], v[98:101], v[216:219], v[78:81]
	v_mfma_f32_16x16x32_bf16 v[66:69], v[150:153], v[216:219], v[66:69]
	v_mfma_f32_16x16x32_bf16 v[130:133], v[134:137], v[196:199], v[130:133]
	v_mfma_f32_16x16x32_bf16 v[118:121], v[154:157], v[196:199], v[118:121]
	v_mfma_f32_16x16x32_bf16 v[114:117], v[134:137], v[204:207], v[114:117]
	v_mfma_f32_16x16x32_bf16 v[102:105], v[154:157], v[204:207], v[102:105]
	v_mfma_f32_16x16x32_bf16 v[94:97], v[134:137], v[212:215], v[94:97]
	v_mfma_f32_16x16x32_bf16 v[82:85], v[154:157], v[212:215], v[82:85]
	v_mfma_f32_16x16x32_bf16 v[78:81], v[134:137], v[220:223], v[78:81]
	v_mfma_f32_16x16x32_bf16 v[66:69], v[154:157], v[220:223], v[66:69]
	v_mfma_f32_16x16x32_bf16 v[126:129], v[158:161], v[192:195], v[126:129]
	v_mfma_f32_16x16x32_bf16 v[122:125], v[184:187], v[192:195], v[122:125]
	v_mfma_f32_16x16x32_bf16 v[110:113], v[158:161], v[200:203], v[110:113]
	v_mfma_f32_16x16x32_bf16 v[106:109], v[184:187], v[200:203], v[106:109]
	v_mfma_f32_16x16x32_bf16 v[90:93], v[158:161], v[208:211], v[90:93]
	v_mfma_f32_16x16x32_bf16 v[86:89], v[184:187], v[208:211], v[86:89]
	v_mfma_f32_16x16x32_bf16 v[74:77], v[158:161], v[216:219], v[74:77]
	v_mfma_f32_16x16x32_bf16 v[70:73], v[184:187], v[216:219], v[70:73]
	v_mfma_f32_16x16x32_bf16 v[126:129], v[180:183], v[196:199], v[126:129]
	v_mfma_f32_16x16x32_bf16 v[122:125], v[188:191], v[196:199], v[122:125]
	v_mfma_f32_16x16x32_bf16 v[110:113], v[180:183], v[204:207], v[110:113]
	v_mfma_f32_16x16x32_bf16 v[106:109], v[188:191], v[204:207], v[106:109]
	v_mfma_f32_16x16x32_bf16 v[90:93], v[180:183], v[212:215], v[90:93]
	v_mfma_f32_16x16x32_bf16 v[86:89], v[188:191], v[212:215], v[86:89]
	v_mfma_f32_16x16x32_bf16 v[74:77], v[180:183], v[220:223], v[74:77]
	v_mfma_f32_16x16x32_bf16 v[70:73], v[188:191], v[220:223], v[70:73]
	s_setprio 0
	s_barrier
; #define PG8_STAGE(bufoff, gbase, voff) do { _Pragma("unroll") for (int _i = 0; _i < 2; ++_i) \
;         __builtin_amdgcn_global_load_lds((const unsigned*)((const char*)(gbase) + (voff)[_i]), (LAS unsigned*)(lds + (bufoff) + ldsw + _i * 8192), 16, 0, 0); } while (0)
; #define PG8_LDA(dst, b, h) do { _Pragma("unroll") for (int m = 0; m < 4; ++m) _Pragma("unroll") for (int k = 0; k < 2; ++k) dst[m][k] = *(const LAS bf16x8*)(lds + PG8_SA(b, h) + aoff + m * 2048 + k * 1024); } while (0)
; #define PG8_MMA(ai, bj, At, Bt) do { __builtin_amdgcn_s_setprio(1); _Pragma("unroll") for (int m = 0; m < 4; ++m) _Pragma("unroll") for (int n = 0; n < 2; ++n) _Pragma("unroll") for (int k = 0; k < 2; ++k) \
;         acc[ai][bj][m][n] = __builtin_amdgcn_mfma_f32_16x16x32_bf16(Bt[n][k], At[m][k], acc[ai][bj][m][n], 0, 0, 0); __builtin_amdgcn_s_setprio(0); } while (0)
; #define PG8_WAIT_V(n) asm volatile("s_waitcnt vmcnt(" #n ")" ::: "memory")
; #define PG8_WAIT_L(n) asm volatile("s_waitcnt lgkmcnt(" #n ")" ::: "memory")
; #define PG8_BAR __builtin_amdgcn_s_barrier()
; #define PG8_SCHED __builtin_amdgcn_sched_barrier(0)
; template <class Epi, class Sched>
; __device__ __forceinline__ void gemm_phase(LAS unsigned char* lds, const Gemm g, const Sched S, const Epi E, const int tid) {
;     ...
;             PG8_LDA(At, 1, 1); PG8_STAGE(PG8_SB(1, 0), b3, voffB); PG8_STAGE(PG8_SB(1, 1), b3 + hstepB, voffB); PG8_STAGE(PG8_SA(1, 0), a3, voffA);
;             PG8_WAIT_V(8); PG8_WAIT_L(0); PG8_BAR; PG8_MMA(1, 0, At, B0); PG8_MMA(1, 1, At, B1); PG8_BAR; PG8_SCHED;
	s_add_i32 s26, s85, s28
	v_lshl_add_u64 v[162:163], v[162:163], 0, s[64:65]
	s_mov_b32 m0, s26
	ds_read_b128 v[192:195], v166 offset:49152
	ds_read_b128 v[196:199], v166 offset:50176
	ds_read_b128 v[200:203], v166 offset:51200
	ds_read_b128 v[204:207], v166 offset:52224
	ds_read_b128 v[208:211], v166 offset:53248
	ds_read_b128 v[212:215], v166 offset:54272
	ds_read_b128 v[216:219], v166 offset:55296
	ds_read_b128 v[220:223], v166 offset:56320
	global_load_lds_dwordx4 v[162:163], off
	s_add_i32 m0, s26, 0x2000
	s_add_u32 s24, s24, 0x40080
	v_lshl_add_u64 v[162:163], v[224:225], 0, s[64:65]
	s_addc_u32 s25, s25, 0
	s_add_i32 s26, s88, s28
	global_load_lds_dwordx4 v[162:163], off
	s_mov_b32 m0, s26
	v_lshl_add_u64 v[162:163], s[24:25], 0, v[142:143]
	global_load_lds_dwordx4 v[162:163], off
	s_add_i32 m0, s26, 0x2000
	v_lshl_add_u64 v[162:163], s[24:25], 0, v[138:139]
	global_load_lds_dwordx4 v[162:163], off
	s_mov_b32 m0, s46
	v_lshl_add_u64 v[162:163], v[226:227], 0, s[64:65]
	global_load_lds_dwordx4 v[162:163], off
	s_mov_b32 m0, s47
	v_lshl_add_u64 v[162:163], v[228:229], 0, s[64:65]
	global_load_lds_dwordx4 v[162:163], off
	s_waitcnt vmcnt(8)
	s_waitcnt lgkmcnt(0)
	s_barrier
	s_setprio 1
	v_mfma_f32_16x16x32_bf16 v[62:65], v[98:101], v[192:195], v[62:65]
	v_mfma_f32_16x16x32_bf16 v[50:53], v[150:153], v[192:195], v[50:53]
	v_mfma_f32_16x16x32_bf16 v[46:49], v[98:101], v[200:203], v[46:49]
	v_mfma_f32_16x16x32_bf16 v[34:37], v[150:153], v[200:203], v[34:37]
	v_mfma_f32_16x16x32_bf16 v[30:33], v[98:101], v[208:211], v[30:33]
	v_mfma_f32_16x16x32_bf16 v[18:21], v[150:153], v[208:211], v[18:21]
	v_mfma_f32_16x16x32_bf16 v[14:17], v[98:101], v[216:219], v[14:17]
	v_mfma_f32_16x16x32_bf16 v[6:9], v[150:153], v[216:219], v[6:9]
	v_mfma_f32_16x16x32_bf16 v[62:65], v[134:137], v[196:199], v[62:65]
	v_mfma_f32_16x16x32_bf16 v[50:53], v[154:157], v[196:199], v[50:53]
	v_mfma_f32_16x16x32_bf16 v[46:49], v[134:137], v[204:207], v[46:49]
	v_mfma_f32_16x16x32_bf16 v[34:37], v[154:157], v[204:207], v[34:37]
	v_mfma_f32_16x16x32_bf16 v[30:33], v[134:137], v[212:215], v[30:33]
	v_mfma_f32_16x16x32_bf16 v[18:21], v[154:157], v[212:215], v[18:21]
	v_mfma_f32_16x16x32_bf16 v[14:17], v[134:137], v[220:223], v[14:17]
	v_mfma_f32_16x16x32_bf16 v[6:9], v[154:157], v[220:223], v[6:9]
	v_mfma_f32_16x16x32_bf16 v[58:61], v[158:161], v[192:195], v[58:61]
	v_mfma_f32_16x16x32_bf16 v[54:57], v[184:187], v[192:195], v[54:57]
	v_mfma_f32_16x16x32_bf16 v[42:45], v[158:161], v[200:203], v[42:45]
	v_mfma_f32_16x16x32_bf16 v[38:41], v[184:187], v[200:203], v[38:41]
	v_mfma_f32_16x16x32_bf16 v[26:29], v[158:161], v[208:211], v[26:29]
	v_mfma_f32_16x16x32_bf16 v[22:25], v[184:187], v[208:211], v[22:25]
	v_mfma_f32_16x16x32_bf16 v[10:13], v[158:161], v[216:219], v[10:13]
	v_mfma_f32_16x16x32_bf16 v[2:5], v[184:187], v[216:219], v[2:5]
	v_mfma_f32_16x16x32_bf16 v[58:61], v[180:183], v[196:199], v[58:61]
	v_mfma_f32_16x16x32_bf16 v[54:57], v[188:191], v[196:199], v[54:57]
	v_mfma_f32_16x16x32_bf16 v[42:45], v[180:183], v[204:207], v[42:45]
	v_mfma_f32_16x16x32_bf16 v[38:41], v[188:191], v[204:207], v[38:41]
	v_mfma_f32_16x16x32_bf16 v[26:29], v[180:183], v[212:215], v[26:29]
	v_mfma_f32_16x16x32_bf16 v[22:25], v[188:191], v[212:215], v[22:25]
	v_mfma_f32_16x16x32_bf16 v[10:13], v[180:183], v[220:223], v[10:13]
	v_mfma_f32_16x16x32_bf16 v[2:5], v[188:191], v[220:223], v[2:5]
	s_setprio 0
	s_barrier
	s_add_i32 s84, s84, 2
	s_add_u32 s82, s82, 0x100
	s_addc_u32 s83, s83, 0
	s_add_u32 s22, s22, 0x100
	s_addc_u32 s23, s23, 0
	s_cmp_gt_u32 s84, 13
	s_cbranch_scc0 .LBB0_819
	s_and_b64 vcc, exec, s[12:13]
	s_cbranch_vccz .LBB0_822
	s_barrier
